# v17
# speedup vs baseline: 1.0044x; 1.0044x over previous
.LBB0_777:
	v_or_b32_e32 v56, s30, v161
	v_mad_u32_u24 v162, v56, s38, 0
	v_lshl_add_u32 v163, v155, 2, v162
	v_or_b32_e32 v56, s30, v160
	ds_read_b128 v[120:123], v163
	ds_read_b128 v[128:131], v163 offset:16
	ds_read_b128 v[88:91], v163 offset:256
	ds_read_b128 v[64:67], v163 offset:272
	ds_read_b128 v[100:103], v163 offset:512
	ds_read_b128 v[76:79], v163 offset:528
	ds_read_b128 v[108:111], v163 offset:768
	ds_read_b128 v[84:87], v163 offset:784
	ds_read_b128 v[138:141], v163 offset:1024
	v_sub_u32_e32 v57, 0xff, v56
	v_cndmask_b32_e64 v56, v57, v56, s[0:1]
	v_add_u32_e32 v56, s33, v56
	v_ashrrev_i32_e32 v57, 31, v56
	s_waitcnt lgkmcnt(0)
	v_pk_mul_f32 v[146:147], v[54:55], v[122:123]
	v_pk_mul_f32 v[122:123], v[50:51], v[122:123]
	v_lshlrev_b64 v[56:57], 12, v[56:57]
	v_lshl_add_u32 v164, v156, 2, v162
	v_pk_fma_f32 v[146:147], v[52:53], v[120:121], v[146:147]
	v_pk_fma_f32 v[120:121], v[48:49], v[120:121], v[122:123]
	v_pk_mul_f32 v[122:123], v[54:55], v[140:141]
	v_pk_mul_f32 v[140:141], v[50:51], v[140:141]
	v_lshl_add_u64 v[134:135], v[132:133], 0, v[56:57]
	v_add_u32_e32 v56, 0x400, v164
	v_pk_fma_f32 v[122:123], v[52:53], v[138:139], v[122:123]
	v_pk_fma_f32 v[138:139], v[48:49], v[138:139], v[140:141]
	v_pk_fma_f32 v[140:141], v[44:45], v[128:129], v[146:147]
	v_pk_fma_f32 v[120:121], v[40:41], v[128:129], v[120:121]
	ds_read2_b64 v[56:59], v56 offset0:32 offset1:228
	ds_read_b128 v[142:145], v163 offset:1040
	ds_read_b128 v[116:119], v163 offset:1568
	ds_read_b128 v[104:107], v163 offset:1584
	ds_read_b128 v[80:83], v163 offset:1824
	ds_read_b128 v[60:63], v163 offset:1840
	ds_read_b128 v[92:95], v163 offset:2080
	ds_read_b128 v[68:71], v163 offset:2096
	ds_read_b128 v[96:99], v163 offset:2336
	ds_read_b128 v[72:75], v163 offset:2352
	ds_read_b128 v[124:127], v163 offset:2592
	ds_read_b128 v[112:115], v163 offset:2608
	ds_read_b64 v[136:137], v162 offset:3104
	s_waitcnt lgkmcnt(0)
	v_pk_fma_f32 v[128:129], v[40:41], v[142:143], v[138:139]
	v_pk_fma_f32 v[138:139], v[46:47], v[130:131], v[140:141]
	v_pk_fma_f32 v[120:121], v[42:43], v[130:131], v[120:121]
	v_add_f32_e32 v121, v120, v121
	v_add_f32_e32 v120, v138, v139
	v_pk_fma_f32 v[122:123], v[44:45], v[142:143], v[122:123]
	v_pk_fma_f32 v[128:129], v[42:43], v[144:145], v[128:129]
	v_add_f32_dpp v120, v120, v120 quad_perm:[1,0,3,2] row_mask:0xf bank_mask:0xf bound_ctrl:1
	v_add_f32_dpp v121, v121, v121 quad_perm:[1,0,3,2] row_mask:0xf bank_mask:0xf bound_ctrl:1
	v_pk_fma_f32 v[122:123], v[46:47], v[144:145], v[122:123]
	v_add_f32_e32 v122, v122, v123
	v_add_f32_e32 v123, v128, v129
	v_add_f32_dpp v120, v120, v120 quad_perm:[2,3,0,1] row_mask:0xf bank_mask:0xf bound_ctrl:1
	v_add_f32_dpp v121, v121, v121 quad_perm:[2,3,0,1] row_mask:0xf bank_mask:0xf bound_ctrl:1
	v_add_f32_dpp v122, v122, v122 quad_perm:[1,0,3,2] row_mask:0xf bank_mask:0xf bound_ctrl:1
	v_add_f32_dpp v123, v123, v123 quad_perm:[1,0,3,2] row_mask:0xf bank_mask:0xf bound_ctrl:1
	v_add_f32_dpp v120, v120, v120 row_half_mirror row_mask:0xf bank_mask:0xf bound_ctrl:1
	v_add_f32_dpp v121, v121, v121 row_half_mirror row_mask:0xf bank_mask:0xf bound_ctrl:1
	v_add_f32_dpp v122, v122, v122 quad_perm:[2,3,0,1] row_mask:0xf bank_mask:0xf bound_ctrl:1
	v_add_f32_dpp v123, v123, v123 quad_perm:[2,3,0,1] row_mask:0xf bank_mask:0xf bound_ctrl:1
	s_nop 0
	v_mov_b32_dpp v128, v122 row_half_mirror row_mask:0xf bank_mask:0xf bound_ctrl:1
	v_mov_b32_dpp v129, v123 row_half_mirror row_mask:0xf bank_mask:0xf bound_ctrl:1
	s_and_saveexec_b64 s[30:31], s[8:9]
	s_cbranch_execz .LBB0_779
	ds_read_b64 v[130:131], v162 offset:1536
	v_pk_add_f32 v[122:123], v[122:123], v[128:129]
	s_waitcnt lgkmcnt(0)
	v_pk_fma_f32 v[122:123], v[56:57], v[130:131], v[122:123] op_sel:[0,1,0]
	s_nop 0
	v_pk_fma_f32 v[122:123], v[120:121], v[130:131], v[122:123] op_sel_hi:[1,0,1] neg_lo:[1,0,0] neg_hi:[1,0,0]
	flat_store_dwordx2 v[134:135], v[122:123]
.LBB0_779:
	s_or_b64 exec, exec, s[30:31]
	v_pk_mul_f32 v[122:123], v[108:109], v[120:121] op_sel_hi:[1,0]
	v_pk_mul_f32 v[108:109], v[108:109], v[120:121] op_sel:[0,1]
	v_pk_fma_f32 v[122:123], v[100:101], v[56:57], v[122:123] op_sel_hi:[1,0,1] neg_lo:[0,0,1] neg_hi:[0,0,1]
	v_pk_fma_f32 v[100:101], v[100:101], v[56:57], v[108:109] op_sel:[0,1,0] neg_lo:[0,0,1] neg_hi:[0,0,1]
	v_pk_fma_f32 v[140:141], v[52:53], v[88:89], v[122:123]
	v_pk_mul_f32 v[52:53], v[110:111], v[120:121] op_sel_hi:[1,0]
	v_pk_fma_f32 v[48:49], v[48:49], v[88:89], v[100:101]
	v_pk_fma_f32 v[52:53], v[102:103], v[56:57], v[52:53] op_sel_hi:[1,0,1] neg_lo:[0,0,1] neg_hi:[0,0,1]
	v_pk_mul_f32 v[88:89], v[110:111], v[120:121] op_sel:[0,1]
	v_pk_fma_f32 v[144:145], v[54:55], v[90:91], v[52:53]
	v_pk_fma_f32 v[88:89], v[102:103], v[56:57], v[88:89] op_sel:[0,1,0] neg_lo:[0,0,1] neg_hi:[0,0,1]
	v_pk_mul_f32 v[52:53], v[84:85], v[120:121] op_sel_hi:[1,0]
	v_pk_fma_f32 v[50:51], v[50:51], v[90:91], v[88:89]
	v_pk_fma_f32 v[52:53], v[76:77], v[56:57], v[52:53] op_sel_hi:[1,0,1] neg_lo:[0,0,1] neg_hi:[0,0,1]
	v_pk_mul_f32 v[54:55], v[84:85], v[120:121] op_sel:[0,1]
	v_pk_fma_f32 v[146:147], v[44:45], v[64:65], v[52:53]
	v_pk_fma_f32 v[54:55], v[76:77], v[56:57], v[54:55] op_sel:[0,1,0] neg_lo:[0,0,1] neg_hi:[0,0,1]
	v_pk_mul_f32 v[44:45], v[86:87], v[120:121] op_sel_hi:[1,0]
	v_pk_mul_f32 v[52:53], v[86:87], v[120:121] op_sel:[0,1]
	v_pk_mul_f32 v[148:149], v[118:119], v[144:145]
	v_pk_mul_f32 v[118:119], v[118:119], v[50:51]
	v_pk_fma_f32 v[40:41], v[40:41], v[64:65], v[54:55]
	v_pk_fma_f32 v[44:45], v[78:79], v[56:57], v[44:45] op_sel_hi:[1,0,1] neg_lo:[0,0,1] neg_hi:[0,0,1]
	v_pk_fma_f32 v[52:53], v[78:79], v[56:57], v[52:53] op_sel:[0,1,0] neg_lo:[0,0,1] neg_hi:[0,0,1]
	v_pk_fma_f32 v[148:149], v[116:117], v[140:141], v[148:149]
	v_pk_fma_f32 v[116:117], v[116:117], v[48:49], v[118:119]
	v_pk_mul_f32 v[118:119], v[126:127], v[144:145]
	v_pk_mul_f32 v[126:127], v[126:127], v[50:51]
	v_pk_fma_f32 v[56:57], v[46:47], v[66:67], v[44:45]
	v_pk_fma_f32 v[42:43], v[42:43], v[66:67], v[52:53]
	v_pk_fma_f32 v[118:119], v[124:125], v[140:141], v[118:119]
	v_pk_fma_f32 v[124:125], v[124:125], v[48:49], v[126:127]
	v_pk_fma_f32 v[126:127], v[104:105], v[146:147], v[148:149]
	v_pk_fma_f32 v[104:105], v[104:105], v[40:41], v[116:117]
	ds_read_b128 v[100:103], v163 offset:3152
	ds_read_b128 v[76:79], v163 offset:3392
	ds_read_b128 v[44:47], v163 offset:3408
	ds_read_b128 v[84:87], v163 offset:3648
	ds_read_b128 v[52:55], v163 offset:3664
	ds_read_b128 v[88:91], v163 offset:3904
	ds_read_b128 v[64:67], v163 offset:3920
	ds_read_b128 v[120:123], v163 offset:4160
	ds_read_b128 v[108:111], v163 offset:4176
	ds_read_b64 v[138:139], v164 offset:4416
	ds_read_b128 v[128:131], v163 offset:3136
	ds_read_b64 v[142:143], v162 offset:4672
	v_pk_fma_f32 v[116:117], v[112:113], v[146:147], v[118:119]
	v_pk_fma_f32 v[112:113], v[112:113], v[40:41], v[124:125]
	v_pk_fma_f32 v[118:119], v[106:107], v[56:57], v[126:127]
	v_pk_fma_f32 v[104:105], v[106:107], v[42:43], v[104:105]
	v_pk_fma_f32 v[106:107], v[114:115], v[56:57], v[116:117]
	v_pk_fma_f32 v[112:113], v[114:115], v[42:43], v[112:113]
	v_add_f32_e32 v105, v104, v105
	v_add_f32_e32 v104, v118, v119
	s_nop 1
	v_add_f32_dpp v104, v104, v104 quad_perm:[1,0,3,2] row_mask:0xf bank_mask:0xf bound_ctrl:1
	v_add_f32_dpp v105, v105, v105 quad_perm:[1,0,3,2] row_mask:0xf bank_mask:0xf bound_ctrl:1
	s_nop 1
	v_add_f32_e32 v106, v106, v107
	v_add_f32_e32 v107, v112, v113
	v_add_f32_dpp v104, v104, v104 quad_perm:[2,3,0,1] row_mask:0xf bank_mask:0xf bound_ctrl:1
	v_add_f32_dpp v105, v105, v105 quad_perm:[2,3,0,1] row_mask:0xf bank_mask:0xf bound_ctrl:1
	v_add_f32_dpp v106, v106, v106 quad_perm:[1,0,3,2] row_mask:0xf bank_mask:0xf bound_ctrl:1
	v_add_f32_dpp v107, v107, v107 quad_perm:[1,0,3,2] row_mask:0xf bank_mask:0xf bound_ctrl:1
	v_add_f32_dpp v104, v104, v104 row_half_mirror row_mask:0xf bank_mask:0xf bound_ctrl:1
	v_add_f32_dpp v105, v105, v105 row_half_mirror row_mask:0xf bank_mask:0xf bound_ctrl:1
	v_add_f32_dpp v106, v106, v106 quad_perm:[2,3,0,1] row_mask:0xf bank_mask:0xf bound_ctrl:1
	v_add_f32_dpp v107, v107, v107 quad_perm:[2,3,0,1] row_mask:0xf bank_mask:0xf bound_ctrl:1
	s_nop 0
	v_mov_b32_dpp v112, v106 row_half_mirror row_mask:0xf bank_mask:0xf bound_ctrl:1
	v_mov_b32_dpp v113, v107 row_half_mirror row_mask:0xf bank_mask:0xf bound_ctrl:1
	s_and_saveexec_b64 s[30:31], s[8:9]
	s_cbranch_execz .LBB0_781
	v_pk_add_f32 v[106:107], v[106:107], v[112:113]
	v_lshl_add_u64 v[112:113], s[36:37], 2, v[134:135]
	v_pk_fma_f32 v[106:107], v[58:59], v[136:137], v[106:107] op_sel:[0,1,0]
	s_nop 0
	v_pk_fma_f32 v[106:107], v[136:137], v[104:105], v[106:107] op_sel_hi:[0,1,1] neg_lo:[1,0,0] neg_hi:[1,0,0]
	flat_store_dwordx2 v[112:113], v[106:107]

.LBB0_785:
	s_or_b64 exec, exec, s[30:31]
	v_pk_mul_f32 v[92:93], v[80:81], v[104:105] op_sel_hi:[1,0]
	v_pk_mul_f32 v[80:81], v[80:81], v[104:105] op_sel:[0,1]
	v_pk_fma_f32 v[92:93], v[72:73], v[136:137], v[92:93] op_sel_hi:[1,0,1] neg_lo:[0,0,1] neg_hi:[0,0,1]
	v_pk_fma_f32 v[80:81], v[72:73], v[136:137], v[80:81] op_sel:[0,1,0] neg_lo:[0,0,1] neg_hi:[0,0,1]
	v_pk_fma_f32 v[72:73], v[68:69], v[88:89], v[92:93]
	v_pk_fma_f32 v[92:93], v[68:69], v[100:101], v[80:81]
	v_pk_mul_f32 v[68:69], v[82:83], v[104:105] op_sel_hi:[1,0]
	v_pk_mul_f32 v[80:81], v[82:83], v[104:105] op_sel:[0,1]
	v_pk_fma_f32 v[68:69], v[74:75], v[136:137], v[68:69] op_sel_hi:[1,0,1] neg_lo:[0,0,1] neg_hi:[0,0,1]
	v_pk_fma_f32 v[80:81], v[74:75], v[136:137], v[80:81] op_sel:[0,1,0] neg_lo:[0,0,1] neg_hi:[0,0,1]
	v_pk_fma_f32 v[74:75], v[70:71], v[90:91], v[68:69]
	v_pk_mul_f32 v[68:69], v[56:57], v[104:105] op_sel_hi:[1,0]
	v_pk_mul_f32 v[56:57], v[56:57], v[104:105] op_sel:[0,1]
	v_pk_fma_f32 v[94:95], v[70:71], v[102:103], v[80:81]
	v_pk_fma_f32 v[68:69], v[48:49], v[136:137], v[68:69] op_sel_hi:[1,0,1] neg_lo:[0,0,1] neg_hi:[0,0,1]
	v_pk_fma_f32 v[48:49], v[48:49], v[136:137], v[56:57] op_sel:[0,1,0] neg_lo:[0,0,1] neg_hi:[0,0,1]
	v_pk_fma_f32 v[140:141], v[40:41], v[130:131], v[68:69]
	v_pk_fma_f32 v[142:143], v[40:41], v[142:143], v[48:49]
	v_pk_mul_f32 v[40:41], v[58:59], v[104:105] op_sel_hi:[1,0]
	v_pk_mul_f32 v[48:49], v[58:59], v[104:105] op_sel:[0,1]
	s_waitcnt lgkmcnt(0)
	v_pk_mul_f32 v[148:149], v[122:123], v[74:75]
	v_pk_mul_f32 v[122:123], v[122:123], v[94:95]
	v_pk_fma_f32 v[40:41], v[50:51], v[136:137], v[40:41] op_sel_hi:[1,0,1] neg_lo:[0,0,1] neg_hi:[0,0,1]
	v_pk_fma_f32 v[48:49], v[50:51], v[136:137], v[48:49] op_sel:[0,1,0] neg_lo:[0,0,1] neg_hi:[0,0,1]
	v_pk_fma_f32 v[148:149], v[120:121], v[72:73], v[148:149]
	v_pk_fma_f32 v[120:121], v[120:121], v[92:93], v[122:123]
	v_pk_mul_f32 v[122:123], v[118:119], v[74:75]
	v_pk_mul_f32 v[118:119], v[118:119], v[94:95]
	v_pk_fma_f32 v[144:145], v[42:43], v[144:145], v[40:41]
	v_pk_fma_f32 v[146:147], v[42:43], v[146:147], v[48:49]
	v_pk_fma_f32 v[122:123], v[116:117], v[72:73], v[122:123]
	v_pk_fma_f32 v[116:117], v[116:117], v[92:93], v[118:119]
	v_pk_fma_f32 v[118:119], v[96:97], v[140:141], v[148:149]
	v_pk_fma_f32 v[96:97], v[96:97], v[142:143], v[120:121]
	ds_read_b128 v[100:103], v163 offset:7856
	ds_read_b128 v[68:71], v163 offset:8096
	ds_read_b128 v[40:43], v163 offset:8112
	ds_read_b128 v[80:83], v163 offset:8352
	ds_read_b128 v[48:51], v163 offset:8368
	ds_read_b128 v[88:91], v163 offset:8608
	ds_read_b128 v[56:59], v163 offset:8624
	ds_read_b128 v[112:115], v163 offset:8864
	ds_read_b128 v[104:107], v163 offset:8880
	ds_read_b64 v[130:131], v164 offset:9120
	ds_read_b128 v[124:127], v163 offset:7840
	ds_read_b64 v[136:137], v162 offset:9376
	v_pk_fma_f32 v[120:121], v[108:109], v[140:141], v[122:123]
	v_pk_fma_f32 v[108:109], v[108:109], v[142:143], v[116:117]
	v_pk_fma_f32 v[116:117], v[98:99], v[144:145], v[118:119]
	v_pk_fma_f32 v[96:97], v[98:99], v[146:147], v[96:97]
	v_pk_fma_f32 v[98:99], v[110:111], v[144:145], v[120:121]
	v_pk_fma_f32 v[108:109], v[110:111], v[146:147], v[108:109]
	v_add_f32_e32 v97, v96, v97
	v_add_f32_e32 v96, v116, v117
	s_nop 1
	v_add_f32_dpp v96, v96, v96 quad_perm:[1,0,3,2] row_mask:0xf bank_mask:0xf bound_ctrl:1
	v_add_f32_dpp v97, v97, v97 quad_perm:[1,0,3,2] row_mask:0xf bank_mask:0xf bound_ctrl:1
	s_nop 1
	v_add_f32_e32 v98, v98, v99
	v_add_f32_e32 v99, v108, v109
	v_add_f32_dpp v96, v96, v96 quad_perm:[2,3,0,1] row_mask:0xf bank_mask:0xf bound_ctrl:1
	v_add_f32_dpp v97, v97, v97 quad_perm:[2,3,0,1] row_mask:0xf bank_mask:0xf bound_ctrl:1
	v_add_f32_dpp v98, v98, v98 quad_perm:[1,0,3,2] row_mask:0xf bank_mask:0xf bound_ctrl:1
	v_add_f32_dpp v99, v99, v99 quad_perm:[1,0,3,2] row_mask:0xf bank_mask:0xf bound_ctrl:1
	v_add_f32_dpp v96, v96, v96 row_half_mirror row_mask:0xf bank_mask:0xf bound_ctrl:1
	v_add_f32_dpp v97, v97, v97 row_half_mirror row_mask:0xf bank_mask:0xf bound_ctrl:1
	v_add_f32_dpp v98, v98, v98 quad_perm:[2,3,0,1] row_mask:0xf bank_mask:0xf bound_ctrl:1
	v_add_f32_dpp v99, v99, v99 quad_perm:[2,3,0,1] row_mask:0xf bank_mask:0xf bound_ctrl:1
	s_nop 0
	v_mov_b32_dpp v108, v98 row_half_mirror row_mask:0xf bank_mask:0xf bound_ctrl:1
	v_mov_b32_dpp v109, v99 row_half_mirror row_mask:0xf bank_mask:0xf bound_ctrl:1
	s_and_saveexec_b64 s[30:31], s[8:9]
	s_cbranch_execz .LBB0_787
	v_pk_add_f32 v[98:99], v[98:99], v[108:109]
	v_readlane_b32 s60, v253, 4
	v_pk_fma_f32 v[98:99], v[128:129], v[138:139], v[98:99] op_sel:[0,1,0]
	v_readlane_b32 s61, v253, 5
	v_pk_fma_f32 v[98:99], v[138:139], v[96:97], v[98:99] op_sel_hi:[0,1,1] neg_lo:[1,0,0] neg_hi:[1,0,0]
	s_nop 0
	v_lshl_add_u64 v[108:109], v[134:135], 0, s[60:61]
	flat_store_dwordx2 v[108:109], v[98:99]
.LBB0_787:
	s_or_b64 exec, exec, s[30:31]
	v_pk_mul_f32 v[98:99], v[84:85], v[96:97] op_sel_hi:[1,0]
	v_pk_mul_f32 v[84:85], v[84:85], v[96:97] op_sel:[0,1]
	v_pk_fma_f32 v[98:99], v[76:77], v[128:129], v[98:99] op_sel_hi:[1,0,1] neg_lo:[0,0,1] neg_hi:[0,0,1]
	v_pk_fma_f32 v[84:85], v[76:77], v[128:129], v[84:85] op_sel:[0,1,0] neg_lo:[0,0,1] neg_hi:[0,0,1]
	v_pk_fma_f32 v[76:77], v[64:65], v[72:73], v[98:99]
	v_pk_mul_f32 v[72:73], v[86:87], v[96:97] op_sel_hi:[1,0]
	v_pk_fma_f32 v[64:65], v[64:65], v[92:93], v[84:85]
	v_pk_fma_f32 v[72:73], v[78:79], v[128:129], v[72:73] op_sel_hi:[1,0,1] neg_lo:[0,0,1] neg_hi:[0,0,1]
	v_pk_mul_f32 v[84:85], v[86:87], v[96:97] op_sel:[0,1]
	s_nop 0
	v_pk_fma_f32 v[84:85], v[78:79], v[128:129], v[84:85] op_sel:[0,1,0] neg_lo:[0,0,1] neg_hi:[0,0,1]
	v_pk_fma_f32 v[78:79], v[66:67], v[74:75], v[72:73]
	v_pk_mul_f32 v[72:73], v[60:61], v[96:97] op_sel_hi:[1,0]
	v_pk_mul_f32 v[60:61], v[60:61], v[96:97] op_sel:[0,1]
	v_pk_fma_f32 v[66:67], v[66:67], v[94:95], v[84:85]
	v_pk_fma_f32 v[72:73], v[52:53], v[128:129], v[72:73] op_sel_hi:[1,0,1] neg_lo:[0,0,1] neg_hi:[0,0,1]
	v_pk_fma_f32 v[52:53], v[52:53], v[128:129], v[60:61] op_sel:[0,1,0] neg_lo:[0,0,1] neg_hi:[0,0,1]
	v_pk_fma_f32 v[140:141], v[44:45], v[140:141], v[72:73]
	v_pk_fma_f32 v[142:143], v[44:45], v[142:143], v[52:53]
	v_pk_mul_f32 v[44:45], v[62:63], v[96:97] op_sel_hi:[1,0]
	v_pk_mul_f32 v[52:53], v[62:63], v[96:97] op_sel:[0,1]
	s_waitcnt lgkmcnt(0)
	v_pk_mul_f32 v[148:149], v[126:127], v[78:79]
	v_pk_mul_f32 v[126:127], v[126:127], v[66:67]
	v_pk_fma_f32 v[44:45], v[54:55], v[128:129], v[44:45] op_sel_hi:[1,0,1] neg_lo:[0,0,1] neg_hi:[0,0,1]
	v_pk_fma_f32 v[52:53], v[54:55], v[128:129], v[52:53] op_sel:[0,1,0] neg_lo:[0,0,1] neg_hi:[0,0,1]
	v_pk_fma_f32 v[148:149], v[124:125], v[76:77], v[148:149]
	v_pk_fma_f32 v[124:125], v[124:125], v[64:65], v[126:127]
	v_pk_mul_f32 v[126:127], v[114:115], v[78:79]
	v_pk_mul_f32 v[114:115], v[114:115], v[66:67]
	v_pk_fma_f32 v[144:145], v[46:47], v[144:145], v[44:45]
	v_pk_fma_f32 v[146:147], v[46:47], v[146:147], v[52:53]
	v_pk_fma_f32 v[126:127], v[112:113], v[76:77], v[126:127]
	v_pk_fma_f32 v[112:113], v[112:113], v[64:65], v[114:115]
	v_pk_fma_f32 v[114:115], v[100:101], v[140:141], v[148:149]
	v_pk_fma_f32 v[100:101], v[100:101], v[142:143], v[124:125]
	ds_read_b128 v[96:99], v163 offset:9424
	ds_read_b128 v[72:75], v163 offset:9664
	ds_read_b128 v[44:47], v163 offset:9680
	ds_read_b128 v[84:87], v163 offset:9920
	ds_read_b128 v[52:55], v163 offset:9936
	ds_read_b128 v[92:95], v163 offset:10176
	ds_read_b128 v[60:63], v163 offset:10192
	ds_read_b128 v[116:119], v163 offset:10432
	ds_read_b128 v[108:111], v163 offset:10448
	ds_read_b64 v[128:129], v164 offset:10688
	ds_read_b128 v[120:123], v163 offset:9408
	ds_read_b64 v[138:139], v162 offset:10944
	v_pk_fma_f32 v[124:125], v[104:105], v[140:141], v[126:127]
	v_pk_fma_f32 v[104:105], v[104:105], v[142:143], v[112:113]
	v_pk_fma_f32 v[112:113], v[102:103], v[144:145], v[114:115]
	v_pk_fma_f32 v[100:101], v[102:103], v[146:147], v[100:101]
	v_pk_fma_f32 v[102:103], v[106:107], v[144:145], v[124:125]
	v_pk_fma_f32 v[104:105], v[106:107], v[146:147], v[104:105]
	v_add_f32_e32 v101, v100, v101
	v_add_f32_e32 v100, v112, v113
	s_nop 1
	v_add_f32_dpp v100, v100, v100 quad_perm:[1,0,3,2] row_mask:0xf bank_mask:0xf bound_ctrl:1
	v_add_f32_dpp v101, v101, v101 quad_perm:[1,0,3,2] row_mask:0xf bank_mask:0xf bound_ctrl:1
	s_nop 1
	v_add_f32_e32 v102, v102, v103
	v_add_f32_e32 v103, v104, v105
	v_add_f32_dpp v100, v100, v100 quad_perm:[2,3,0,1] row_mask:0xf bank_mask:0xf bound_ctrl:1
	v_add_f32_dpp v101, v101, v101 quad_perm:[2,3,0,1] row_mask:0xf bank_mask:0xf bound_ctrl:1
	v_add_f32_dpp v102, v102, v102 quad_perm:[1,0,3,2] row_mask:0xf bank_mask:0xf bound_ctrl:1
	v_add_f32_dpp v103, v103, v103 quad_perm:[1,0,3,2] row_mask:0xf bank_mask:0xf bound_ctrl:1
	v_add_f32_dpp v100, v100, v100 row_half_mirror row_mask:0xf bank_mask:0xf bound_ctrl:1
	v_add_f32_dpp v101, v101, v101 row_half_mirror row_mask:0xf bank_mask:0xf bound_ctrl:1
	v_add_f32_dpp v102, v102, v102 quad_perm:[2,3,0,1] row_mask:0xf bank_mask:0xf bound_ctrl:1
	v_add_f32_dpp v103, v103, v103 quad_perm:[2,3,0,1] row_mask:0xf bank_mask:0xf bound_ctrl:1
	s_nop 0
	v_mov_b32_dpp v104, v102 row_half_mirror row_mask:0xf bank_mask:0xf bound_ctrl:1
	v_mov_b32_dpp v105, v103 row_half_mirror row_mask:0xf bank_mask:0xf bound_ctrl:1
	s_and_saveexec_b64 s[30:31], s[8:9]
	s_cbranch_execz .LBB0_789
	v_pk_add_f32 v[102:103], v[102:103], v[104:105]
	v_readlane_b32 s60, v253, 60
	v_pk_fma_f32 v[102:103], v[130:131], v[136:137], v[102:103] op_sel:[0,1,0]
	v_readlane_b32 s61, v253, 61
	v_pk_fma_f32 v[102:103], v[136:137], v[100:101], v[102:103] op_sel_hi:[0,1,1] neg_lo:[1,0,0] neg_hi:[1,0,0]
	s_nop 0
	v_lshl_add_u64 v[104:105], v[134:135], 0, s[60:61]
	flat_store_dwordx2 v[104:105], v[102:103]

.LBB0_793:
	s_or_b64 exec, exec, s[30:31]
	v_pk_mul_f32 v[100:101], v[88:89], v[104:105] op_sel_hi:[1,0]
	v_pk_mul_f32 v[88:89], v[88:89], v[104:105] op_sel:[0,1]
	v_pk_fma_f32 v[100:101], v[80:81], v[130:131], v[100:101] op_sel_hi:[1,0,1] neg_lo:[0,0,1] neg_hi:[0,0,1]
	v_pk_fma_f32 v[80:81], v[80:81], v[130:131], v[88:89] op_sel:[0,1,0] neg_lo:[0,0,1] neg_hi:[0,0,1]
	v_pk_fma_f32 v[100:101], v[76:77], v[96:97], v[100:101]
	v_pk_fma_f32 v[102:103], v[76:77], v[98:99], v[80:81]
	v_pk_mul_f32 v[76:77], v[90:91], v[104:105] op_sel_hi:[1,0]
	v_pk_mul_f32 v[80:81], v[90:91], v[104:105] op_sel:[0,1]
	v_pk_fma_f32 v[76:77], v[82:83], v[130:131], v[76:77] op_sel_hi:[1,0,1] neg_lo:[0,0,1] neg_hi:[0,0,1]
	v_pk_fma_f32 v[80:81], v[82:83], v[130:131], v[80:81] op_sel:[0,1,0] neg_lo:[0,0,1] neg_hi:[0,0,1]
	v_pk_fma_f32 v[136:137], v[78:79], v[144:145], v[76:77]
	v_pk_mul_f32 v[76:77], v[64:65], v[104:105] op_sel_hi:[1,0]
	v_pk_mul_f32 v[64:65], v[64:65], v[104:105] op_sel:[0,1]
	v_pk_fma_f32 v[140:141], v[78:79], v[146:147], v[80:81]
	v_pk_fma_f32 v[76:77], v[56:57], v[130:131], v[76:77] op_sel_hi:[1,0,1] neg_lo:[0,0,1] neg_hi:[0,0,1]
	v_pk_fma_f32 v[56:57], v[56:57], v[130:131], v[64:65] op_sel:[0,1,0] neg_lo:[0,0,1] neg_hi:[0,0,1]
	v_pk_fma_f32 v[142:143], v[48:49], v[148:149], v[76:77]
	v_pk_fma_f32 v[144:145], v[48:49], v[44:45], v[56:57]
	v_pk_mul_f32 v[44:45], v[66:67], v[104:105] op_sel_hi:[1,0]
	v_pk_mul_f32 v[48:49], v[66:67], v[104:105] op_sel:[0,1]
	s_waitcnt lgkmcnt(0)
	v_pk_mul_f32 v[148:149], v[122:123], v[136:137]
	v_pk_mul_f32 v[122:123], v[122:123], v[140:141]
	v_pk_fma_f32 v[44:45], v[58:59], v[130:131], v[44:45] op_sel_hi:[1,0,1] neg_lo:[0,0,1] neg_hi:[0,0,1]
	v_pk_fma_f32 v[48:49], v[58:59], v[130:131], v[48:49] op_sel:[0,1,0] neg_lo:[0,0,1] neg_hi:[0,0,1]
	v_pk_fma_f32 v[148:149], v[120:121], v[100:101], v[148:149]
	v_pk_fma_f32 v[120:121], v[120:121], v[102:103], v[122:123]
	v_pk_mul_f32 v[122:123], v[118:119], v[136:137]
	v_pk_mul_f32 v[118:119], v[118:119], v[140:141]
	v_pk_fma_f32 v[130:131], v[50:51], v[150:151], v[44:45]
	v_pk_fma_f32 v[146:147], v[50:51], v[46:47], v[48:49]
	v_pk_fma_f32 v[122:123], v[116:117], v[100:101], v[122:123]
	v_pk_fma_f32 v[116:117], v[116:117], v[102:103], v[118:119]
	v_pk_fma_f32 v[118:119], v[92:93], v[142:143], v[148:149]
	v_pk_fma_f32 v[92:93], v[92:93], v[144:145], v[120:121]
	ds_read_b128 v[88:91], v163 offset:14128
	ds_read_b128 v[64:67], v163 offset:14368
	ds_read_b128 v[44:47], v163 offset:14384
	ds_read_b128 v[76:79], v163 offset:14624
	ds_read_b128 v[48:51], v163 offset:14640
	ds_read_b128 v[80:83], v163 offset:14880
	ds_read_b128 v[56:59], v163 offset:14896
	ds_read_b128 v[104:107], v163 offset:15136
	ds_read_b128 v[96:99], v163 offset:15152
	ds_read_b64 v[124:125], v164 offset:15392
	ds_read_b128 v[112:115], v163 offset:14112
	ds_read_b64 v[126:127], v162 offset:15648
	v_pk_fma_f32 v[120:121], v[108:109], v[142:143], v[122:123]
	v_pk_fma_f32 v[108:109], v[108:109], v[144:145], v[116:117]
	v_pk_fma_f32 v[116:117], v[94:95], v[130:131], v[118:119]
	v_pk_fma_f32 v[92:93], v[94:95], v[146:147], v[92:93]
	v_pk_fma_f32 v[94:95], v[110:111], v[130:131], v[120:121]
	v_pk_fma_f32 v[108:109], v[110:111], v[146:147], v[108:109]
	v_add_f32_e32 v93, v92, v93
	v_add_f32_e32 v92, v116, v117
	s_nop 1
	v_add_f32_dpp v92, v92, v92 quad_perm:[1,0,3,2] row_mask:0xf bank_mask:0xf bound_ctrl:1
	v_add_f32_dpp v93, v93, v93 quad_perm:[1,0,3,2] row_mask:0xf bank_mask:0xf bound_ctrl:1
	s_nop 1
	v_add_f32_e32 v94, v94, v95
	v_add_f32_e32 v95, v108, v109
	v_add_f32_dpp v92, v92, v92 quad_perm:[2,3,0,1] row_mask:0xf bank_mask:0xf bound_ctrl:1
	v_add_f32_dpp v93, v93, v93 quad_perm:[2,3,0,1] row_mask:0xf bank_mask:0xf bound_ctrl:1
	v_add_f32_dpp v94, v94, v94 quad_perm:[1,0,3,2] row_mask:0xf bank_mask:0xf bound_ctrl:1
	v_add_f32_dpp v95, v95, v95 quad_perm:[1,0,3,2] row_mask:0xf bank_mask:0xf bound_ctrl:1
	v_add_f32_dpp v92, v92, v92 row_half_mirror row_mask:0xf bank_mask:0xf bound_ctrl:1
	v_add_f32_dpp v93, v93, v93 row_half_mirror row_mask:0xf bank_mask:0xf bound_ctrl:1
	v_add_f32_dpp v94, v94, v94 quad_perm:[2,3,0,1] row_mask:0xf bank_mask:0xf bound_ctrl:1
	v_add_f32_dpp v95, v95, v95 quad_perm:[2,3,0,1] row_mask:0xf bank_mask:0xf bound_ctrl:1
	s_nop 0
	v_mov_b32_dpp v108, v94 row_half_mirror row_mask:0xf bank_mask:0xf bound_ctrl:1
	v_mov_b32_dpp v109, v95 row_half_mirror row_mask:0xf bank_mask:0xf bound_ctrl:1
	s_and_saveexec_b64 s[30:31], s[8:9]
	s_cbranch_execz .LBB0_795
	v_pk_add_f32 v[94:95], v[94:95], v[108:109]
	v_readlane_b32 s60, v253, 6
	v_pk_fma_f32 v[94:95], v[128:129], v[138:139], v[94:95] op_sel:[0,1,0]
	v_readlane_b32 s61, v253, 7
	v_pk_fma_f32 v[94:95], v[138:139], v[92:93], v[94:95] op_sel_hi:[0,1,1] neg_lo:[1,0,0] neg_hi:[1,0,0]
	s_nop 0
	v_lshl_add_u64 v[108:109], v[134:135], 0, s[60:61]
	flat_store_dwordx2 v[108:109], v[94:95]
.LBB0_795:
	s_or_b64 exec, exec, s[30:31]
	v_pk_mul_f32 v[94:95], v[84:85], v[92:93] op_sel_hi:[1,0]
	v_pk_mul_f32 v[84:85], v[84:85], v[92:93] op_sel:[0,1]
	v_pk_fma_f32 v[94:95], v[72:73], v[128:129], v[94:95] op_sel_hi:[1,0,1] neg_lo:[0,0,1] neg_hi:[0,0,1]
	v_pk_fma_f32 v[72:73], v[72:73], v[128:129], v[84:85] op_sel:[0,1,0] neg_lo:[0,0,1] neg_hi:[0,0,1]
	v_pk_fma_f32 v[122:123], v[68:69], v[100:101], v[94:95]
	v_pk_fma_f32 v[138:139], v[68:69], v[102:103], v[72:73]
	v_pk_mul_f32 v[68:69], v[86:87], v[92:93] op_sel_hi:[1,0]
	v_pk_mul_f32 v[72:73], v[86:87], v[92:93] op_sel:[0,1]
	v_pk_fma_f32 v[68:69], v[74:75], v[128:129], v[68:69] op_sel_hi:[1,0,1] neg_lo:[0,0,1] neg_hi:[0,0,1]
	v_pk_fma_f32 v[72:73], v[74:75], v[128:129], v[72:73] op_sel:[0,1,0] neg_lo:[0,0,1] neg_hi:[0,0,1]
	v_pk_fma_f32 v[136:137], v[70:71], v[136:137], v[68:69]
	v_pk_mul_f32 v[68:69], v[60:61], v[92:93] op_sel_hi:[1,0]
	v_pk_mul_f32 v[60:61], v[60:61], v[92:93] op_sel:[0,1]
	v_pk_fma_f32 v[140:141], v[70:71], v[140:141], v[72:73]
	v_pk_fma_f32 v[68:69], v[52:53], v[128:129], v[68:69] op_sel_hi:[1,0,1] neg_lo:[0,0,1] neg_hi:[0,0,1]
	v_pk_fma_f32 v[52:53], v[52:53], v[128:129], v[60:61] op_sel:[0,1,0] neg_lo:[0,0,1] neg_hi:[0,0,1]
	v_pk_fma_f32 v[142:143], v[40:41], v[142:143], v[68:69]
	v_pk_fma_f32 v[144:145], v[40:41], v[144:145], v[52:53]
	v_pk_mul_f32 v[40:41], v[62:63], v[92:93] op_sel_hi:[1,0]
	v_pk_mul_f32 v[52:53], v[62:63], v[92:93] op_sel:[0,1]
	s_waitcnt lgkmcnt(0)
	v_pk_mul_f32 v[148:149], v[114:115], v[136:137]
	v_pk_mul_f32 v[114:115], v[114:115], v[140:141]
	v_pk_fma_f32 v[40:41], v[54:55], v[128:129], v[40:41] op_sel_hi:[1,0,1] neg_lo:[0,0,1] neg_hi:[0,0,1]
	v_pk_fma_f32 v[52:53], v[54:55], v[128:129], v[52:53] op_sel:[0,1,0] neg_lo:[0,0,1] neg_hi:[0,0,1]
	v_pk_fma_f32 v[148:149], v[112:113], v[122:123], v[148:149]
	v_pk_fma_f32 v[112:113], v[112:113], v[138:139], v[114:115]
	v_pk_mul_f32 v[114:115], v[106:107], v[136:137]
	v_pk_mul_f32 v[106:107], v[106:107], v[140:141]
	v_pk_fma_f32 v[130:131], v[42:43], v[130:131], v[40:41]
	v_pk_fma_f32 v[146:147], v[42:43], v[146:147], v[52:53]
	v_pk_fma_f32 v[114:115], v[104:105], v[122:123], v[114:115]
	v_pk_fma_f32 v[104:105], v[104:105], v[138:139], v[106:107]
	v_pk_fma_f32 v[106:107], v[88:89], v[142:143], v[148:149]
	v_pk_fma_f32 v[88:89], v[88:89], v[144:145], v[112:113]
	ds_read_b128 v[92:95], v163 offset:15696
	ds_read_b128 v[68:71], v163 offset:15936
	ds_read_b128 v[40:43], v163 offset:15952
	ds_read_b128 v[72:75], v163 offset:16192
	ds_read_b128 v[52:55], v163 offset:16208
	ds_read_b128 v[84:87], v163 offset:16448
	ds_read_b128 v[60:63], v163 offset:16464
	ds_read_b128 v[108:111], v163 offset:16704
	ds_read_b128 v[100:103], v163 offset:16720
	ds_read_b64 v[120:121], v164 offset:16960
	ds_read_b128 v[116:119], v163 offset:15680
	ds_read_b64 v[128:129], v162 offset:17216
	v_pk_fma_f32 v[112:113], v[96:97], v[142:143], v[114:115]
	v_pk_fma_f32 v[96:97], v[96:97], v[144:145], v[104:105]
	v_pk_fma_f32 v[104:105], v[90:91], v[130:131], v[106:107]
	v_pk_fma_f32 v[88:89], v[90:91], v[146:147], v[88:89]
	v_pk_fma_f32 v[90:91], v[98:99], v[130:131], v[112:113]
	v_pk_fma_f32 v[96:97], v[98:99], v[146:147], v[96:97]
	v_add_f32_e32 v89, v88, v89
	v_add_f32_e32 v88, v104, v105
	s_nop 1
	v_add_f32_dpp v88, v88, v88 quad_perm:[1,0,3,2] row_mask:0xf bank_mask:0xf bound_ctrl:1
	v_add_f32_dpp v89, v89, v89 quad_perm:[1,0,3,2] row_mask:0xf bank_mask:0xf bound_ctrl:1
	s_nop 1
	v_add_f32_e32 v90, v90, v91
	v_add_f32_e32 v91, v96, v97
	v_add_f32_dpp v88, v88, v88 quad_perm:[2,3,0,1] row_mask:0xf bank_mask:0xf bound_ctrl:1
	v_add_f32_dpp v89, v89, v89 quad_perm:[2,3,0,1] row_mask:0xf bank_mask:0xf bound_ctrl:1
	v_add_f32_dpp v90, v90, v90 quad_perm:[1,0,3,2] row_mask:0xf bank_mask:0xf bound_ctrl:1
	v_add_f32_dpp v91, v91, v91 quad_perm:[1,0,3,2] row_mask:0xf bank_mask:0xf bound_ctrl:1
	v_add_f32_dpp v88, v88, v88 row_half_mirror row_mask:0xf bank_mask:0xf bound_ctrl:1
	v_add_f32_dpp v89, v89, v89 row_half_mirror row_mask:0xf bank_mask:0xf bound_ctrl:1
	v_add_f32_dpp v90, v90, v90 quad_perm:[2,3,0,1] row_mask:0xf bank_mask:0xf bound_ctrl:1
	v_add_f32_dpp v91, v91, v91 quad_perm:[2,3,0,1] row_mask:0xf bank_mask:0xf bound_ctrl:1
	s_nop 0
	v_mov_b32_dpp v96, v90 row_half_mirror row_mask:0xf bank_mask:0xf bound_ctrl:1
	v_mov_b32_dpp v97, v91 row_half_mirror row_mask:0xf bank_mask:0xf bound_ctrl:1
	s_and_saveexec_b64 s[30:31], s[8:9]
	s_cbranch_execz .LBB0_797
	v_pk_add_f32 v[90:91], v[90:91], v[96:97]
	v_lshl_add_u64 v[96:97], v[134:135], 0, s[42:43]
	v_pk_fma_f32 v[90:91], v[124:125], v[126:127], v[90:91] op_sel:[0,1,0]
	s_nop 0
	v_pk_fma_f32 v[90:91], v[126:127], v[88:89], v[90:91] op_sel_hi:[0,1,1] neg_lo:[1,0,0] neg_hi:[1,0,0]
	flat_store_dwordx2 v[96:97], v[90:91]
.LBB0_797:
	s_or_b64 exec, exec, s[30:31]
	v_pk_mul_f32 v[90:91], v[80:81], v[88:89] op_sel_hi:[1,0]
	v_pk_mul_f32 v[80:81], v[80:81], v[88:89] op_sel:[0,1]
	v_pk_fma_f32 v[90:91], v[76:77], v[124:125], v[90:91] op_sel_hi:[1,0,1] neg_lo:[0,0,1] neg_hi:[0,0,1]
	v_pk_fma_f32 v[76:77], v[76:77], v[124:125], v[80:81] op_sel:[0,1,0] neg_lo:[0,0,1] neg_hi:[0,0,1]
	v_pk_fma_f32 v[126:127], v[64:65], v[122:123], v[90:91]
	v_pk_fma_f32 v[138:139], v[64:65], v[138:139], v[76:77]
	v_pk_mul_f32 v[64:65], v[82:83], v[88:89] op_sel_hi:[1,0]
	v_pk_mul_f32 v[76:77], v[82:83], v[88:89] op_sel:[0,1]
	v_pk_fma_f32 v[64:65], v[78:79], v[124:125], v[64:65] op_sel_hi:[1,0,1] neg_lo:[0,0,1] neg_hi:[0,0,1]
	v_pk_fma_f32 v[76:77], v[78:79], v[124:125], v[76:77] op_sel:[0,1,0] neg_lo:[0,0,1] neg_hi:[0,0,1]
	v_pk_fma_f32 v[136:137], v[66:67], v[136:137], v[64:65]
	v_pk_mul_f32 v[64:65], v[56:57], v[88:89] op_sel_hi:[1,0]
	v_pk_mul_f32 v[56:57], v[56:57], v[88:89] op_sel:[0,1]
	v_pk_fma_f32 v[140:141], v[66:67], v[140:141], v[76:77]
	v_pk_fma_f32 v[64:65], v[48:49], v[124:125], v[64:65] op_sel_hi:[1,0,1] neg_lo:[0,0,1] neg_hi:[0,0,1]
	v_pk_fma_f32 v[48:49], v[48:49], v[124:125], v[56:57] op_sel:[0,1,0] neg_lo:[0,0,1] neg_hi:[0,0,1]
	v_pk_fma_f32 v[142:143], v[44:45], v[142:143], v[64:65]
	v_pk_fma_f32 v[144:145], v[44:45], v[144:145], v[48:49]
	v_pk_mul_f32 v[44:45], v[58:59], v[88:89] op_sel_hi:[1,0]
	v_pk_mul_f32 v[48:49], v[58:59], v[88:89] op_sel:[0,1]
	s_waitcnt lgkmcnt(0)
	v_pk_mul_f32 v[148:149], v[118:119], v[136:137]
	v_pk_mul_f32 v[118:119], v[118:119], v[140:141]
	v_pk_fma_f32 v[44:45], v[50:51], v[124:125], v[44:45] op_sel_hi:[1,0,1] neg_lo:[0,0,1] neg_hi:[0,0,1]
	v_pk_fma_f32 v[48:49], v[50:51], v[124:125], v[48:49] op_sel:[0,1,0] neg_lo:[0,0,1] neg_hi:[0,0,1]
	v_pk_fma_f32 v[148:149], v[116:117], v[126:127], v[148:149]
	v_pk_fma_f32 v[116:117], v[116:117], v[138:139], v[118:119]
	v_pk_mul_f32 v[118:119], v[110:111], v[136:137]
	v_pk_mul_f32 v[110:111], v[110:111], v[140:141]
	v_pk_fma_f32 v[130:131], v[46:47], v[130:131], v[44:45]
	v_pk_fma_f32 v[146:147], v[46:47], v[146:147], v[48:49]
	v_pk_fma_f32 v[118:119], v[108:109], v[126:127], v[118:119]
	v_pk_fma_f32 v[108:109], v[108:109], v[138:139], v[110:111]
	v_pk_fma_f32 v[110:111], v[92:93], v[142:143], v[148:149]
	v_pk_fma_f32 v[92:93], v[92:93], v[144:145], v[116:117]
	ds_read_b128 v[88:91], v163 offset:17264
	ds_read_b128 v[64:67], v163 offset:17504
	ds_read_b128 v[44:47], v163 offset:17520
	ds_read_b128 v[76:79], v163 offset:17760
	ds_read_b128 v[48:51], v163 offset:17776
	ds_read_b128 v[80:83], v163 offset:18016
	ds_read_b128 v[56:59], v163 offset:18032
	ds_read_b128 v[104:107], v163 offset:18272
	ds_read_b128 v[96:99], v163 offset:18288
	ds_read_b64 v[122:123], v164 offset:18528
	ds_read_b128 v[112:115], v163 offset:17248
	ds_read_b64 v[124:125], v162 offset:18784
	v_pk_fma_f32 v[116:117], v[100:101], v[142:143], v[118:119]
	v_pk_fma_f32 v[100:101], v[100:101], v[144:145], v[108:109]
	v_pk_fma_f32 v[108:109], v[94:95], v[130:131], v[110:111]
	v_pk_fma_f32 v[92:93], v[94:95], v[146:147], v[92:93]
	v_pk_fma_f32 v[94:95], v[102:103], v[130:131], v[116:117]
	v_pk_fma_f32 v[100:101], v[102:103], v[146:147], v[100:101]
	v_add_f32_e32 v93, v92, v93
	v_add_f32_e32 v92, v108, v109
	s_nop 1
	v_add_f32_dpp v92, v92, v92 quad_perm:[1,0,3,2] row_mask:0xf bank_mask:0xf bound_ctrl:1
	v_add_f32_dpp v93, v93, v93 quad_perm:[1,0,3,2] row_mask:0xf bank_mask:0xf bound_ctrl:1
	s_nop 1
	v_add_f32_e32 v94, v94, v95
	v_add_f32_e32 v95, v100, v101
	v_add_f32_dpp v92, v92, v92 quad_perm:[2,3,0,1] row_mask:0xf bank_mask:0xf bound_ctrl:1
	v_add_f32_dpp v93, v93, v93 quad_perm:[2,3,0,1] row_mask:0xf bank_mask:0xf bound_ctrl:1
	v_add_f32_dpp v94, v94, v94 quad_perm:[1,0,3,2] row_mask:0xf bank_mask:0xf bound_ctrl:1
	v_add_f32_dpp v95, v95, v95 quad_perm:[1,0,3,2] row_mask:0xf bank_mask:0xf bound_ctrl:1
	v_add_f32_dpp v92, v92, v92 row_half_mirror row_mask:0xf bank_mask:0xf bound_ctrl:1
	v_add_f32_dpp v93, v93, v93 row_half_mirror row_mask:0xf bank_mask:0xf bound_ctrl:1
	v_add_f32_dpp v94, v94, v94 quad_perm:[2,3,0,1] row_mask:0xf bank_mask:0xf bound_ctrl:1
	v_add_f32_dpp v95, v95, v95 quad_perm:[2,3,0,1] row_mask:0xf bank_mask:0xf bound_ctrl:1
	s_nop 0
	v_mov_b32_dpp v100, v94 row_half_mirror row_mask:0xf bank_mask:0xf bound_ctrl:1
	v_mov_b32_dpp v101, v95 row_half_mirror row_mask:0xf bank_mask:0xf bound_ctrl:1
	s_and_saveexec_b64 s[30:31], s[8:9]
	s_cbranch_execz .LBB0_799
	v_pk_add_f32 v[94:95], v[94:95], v[100:101]
	v_lshl_add_u64 v[100:101], v[134:135], 0, s[44:45]
	v_pk_fma_f32 v[94:95], v[120:121], v[128:129], v[94:95] op_sel:[0,1,0]
	s_nop 0
	v_pk_fma_f32 v[94:95], v[128:129], v[92:93], v[94:95] op_sel_hi:[0,1,1] neg_lo:[1,0,0] neg_hi:[1,0,0]
	flat_store_dwordx2 v[100:101], v[94:95]
.LBB0_799:
	s_or_b64 exec, exec, s[30:31]
	v_pk_mul_f32 v[94:95], v[84:85], v[92:93] op_sel_hi:[1,0]
	v_pk_mul_f32 v[84:85], v[84:85], v[92:93] op_sel:[0,1]
	v_pk_fma_f32 v[94:95], v[72:73], v[120:121], v[94:95] op_sel_hi:[1,0,1] neg_lo:[0,0,1] neg_hi:[0,0,1]
	v_pk_fma_f32 v[72:73], v[72:73], v[120:121], v[84:85] op_sel:[0,1,0] neg_lo:[0,0,1] neg_hi:[0,0,1]
	v_pk_fma_f32 v[128:129], v[68:69], v[126:127], v[94:95]
	v_pk_fma_f32 v[138:139], v[68:69], v[138:139], v[72:73]
	v_pk_mul_f32 v[68:69], v[86:87], v[92:93] op_sel_hi:[1,0]
	v_pk_mul_f32 v[72:73], v[86:87], v[92:93] op_sel:[0,1]
	v_pk_fma_f32 v[68:69], v[74:75], v[120:121], v[68:69] op_sel_hi:[1,0,1] neg_lo:[0,0,1] neg_hi:[0,0,1]
	v_pk_fma_f32 v[72:73], v[74:75], v[120:121], v[72:73] op_sel:[0,1,0] neg_lo:[0,0,1] neg_hi:[0,0,1]
	v_pk_fma_f32 v[136:137], v[70:71], v[136:137], v[68:69]
	v_pk_mul_f32 v[68:69], v[60:61], v[92:93] op_sel_hi:[1,0]
	v_pk_mul_f32 v[60:61], v[60:61], v[92:93] op_sel:[0,1]
	v_pk_fma_f32 v[140:141], v[70:71], v[140:141], v[72:73]
	v_pk_fma_f32 v[68:69], v[52:53], v[120:121], v[68:69] op_sel_hi:[1,0,1] neg_lo:[0,0,1] neg_hi:[0,0,1]
	v_pk_fma_f32 v[52:53], v[52:53], v[120:121], v[60:61] op_sel:[0,1,0] neg_lo:[0,0,1] neg_hi:[0,0,1]
	v_pk_fma_f32 v[142:143], v[40:41], v[142:143], v[68:69]
	v_pk_fma_f32 v[144:145], v[40:41], v[144:145], v[52:53]
	v_pk_mul_f32 v[40:41], v[62:63], v[92:93] op_sel_hi:[1,0]
	v_pk_mul_f32 v[52:53], v[62:63], v[92:93] op_sel:[0,1]
	s_waitcnt lgkmcnt(0)
	v_pk_mul_f32 v[148:149], v[114:115], v[136:137]
	v_pk_mul_f32 v[114:115], v[114:115], v[140:141]
	v_pk_fma_f32 v[40:41], v[54:55], v[120:121], v[40:41] op_sel_hi:[1,0,1] neg_lo:[0,0,1] neg_hi:[0,0,1]
	v_pk_fma_f32 v[52:53], v[54:55], v[120:121], v[52:53] op_sel:[0,1,0] neg_lo:[0,0,1] neg_hi:[0,0,1]
	v_pk_fma_f32 v[148:149], v[112:113], v[128:129], v[148:149]
	v_pk_fma_f32 v[112:113], v[112:113], v[138:139], v[114:115]
	v_pk_mul_f32 v[114:115], v[106:107], v[136:137]
	v_pk_mul_f32 v[106:107], v[106:107], v[140:141]
	v_pk_fma_f32 v[130:131], v[42:43], v[130:131], v[40:41]
	v_pk_fma_f32 v[146:147], v[42:43], v[146:147], v[52:53]
	v_pk_fma_f32 v[114:115], v[104:105], v[128:129], v[114:115]
	v_pk_fma_f32 v[104:105], v[104:105], v[138:139], v[106:107]
	v_pk_fma_f32 v[106:107], v[88:89], v[142:143], v[148:149]
	v_pk_fma_f32 v[88:89], v[88:89], v[144:145], v[112:113]
	ds_read_b128 v[92:95], v163 offset:18832
	ds_read_b128 v[68:71], v163 offset:19072
	ds_read_b128 v[40:43], v163 offset:19088
	ds_read_b128 v[72:75], v163 offset:19328
	ds_read_b128 v[52:55], v163 offset:19344
	ds_read_b128 v[84:87], v163 offset:19584
	ds_read_b128 v[60:63], v163 offset:19600
	ds_read_b128 v[108:111], v163 offset:19840
	ds_read_b128 v[100:103], v163 offset:19856
	ds_read_b64 v[120:121], v164 offset:20096
	ds_read_b128 v[116:119], v163 offset:18816
	ds_read_b64 v[126:127], v162 offset:20352
	v_pk_fma_f32 v[112:113], v[96:97], v[142:143], v[114:115]
	v_pk_fma_f32 v[96:97], v[96:97], v[144:145], v[104:105]
	v_pk_fma_f32 v[104:105], v[90:91], v[130:131], v[106:107]
	v_pk_fma_f32 v[88:89], v[90:91], v[146:147], v[88:89]
	v_pk_fma_f32 v[90:91], v[98:99], v[130:131], v[112:113]
	v_pk_fma_f32 v[96:97], v[98:99], v[146:147], v[96:97]
	v_add_f32_e32 v89, v88, v89
	v_add_f32_e32 v88, v104, v105
	s_nop 1
	v_add_f32_dpp v88, v88, v88 quad_perm:[1,0,3,2] row_mask:0xf bank_mask:0xf bound_ctrl:1
	v_add_f32_dpp v89, v89, v89 quad_perm:[1,0,3,2] row_mask:0xf bank_mask:0xf bound_ctrl:1
	s_nop 1
	v_add_f32_e32 v90, v90, v91
	v_add_f32_e32 v91, v96, v97
	v_add_f32_dpp v88, v88, v88 quad_perm:[2,3,0,1] row_mask:0xf bank_mask:0xf bound_ctrl:1
	v_add_f32_dpp v89, v89, v89 quad_perm:[2,3,0,1] row_mask:0xf bank_mask:0xf bound_ctrl:1
	v_add_f32_dpp v90, v90, v90 quad_perm:[1,0,3,2] row_mask:0xf bank_mask:0xf bound_ctrl:1
	v_add_f32_dpp v91, v91, v91 quad_perm:[1,0,3,2] row_mask:0xf bank_mask:0xf bound_ctrl:1
	v_add_f32_dpp v88, v88, v88 row_half_mirror row_mask:0xf bank_mask:0xf bound_ctrl:1
	v_add_f32_dpp v89, v89, v89 row_half_mirror row_mask:0xf bank_mask:0xf bound_ctrl:1
	v_add_f32_dpp v90, v90, v90 quad_perm:[2,3,0,1] row_mask:0xf bank_mask:0xf bound_ctrl:1
	v_add_f32_dpp v91, v91, v91 quad_perm:[2,3,0,1] row_mask:0xf bank_mask:0xf bound_ctrl:1
	s_nop 0
	v_mov_b32_dpp v96, v90 row_half_mirror row_mask:0xf bank_mask:0xf bound_ctrl:1
	v_mov_b32_dpp v97, v91 row_half_mirror row_mask:0xf bank_mask:0xf bound_ctrl:1
	s_and_saveexec_b64 s[30:31], s[8:9]
	s_cbranch_execz .LBB0_801
	v_pk_add_f32 v[90:91], v[90:91], v[96:97]
	v_lshl_add_u64 v[96:97], v[134:135], 0, s[46:47]
	v_pk_fma_f32 v[90:91], v[122:123], v[124:125], v[90:91] op_sel:[0,1,0]
	s_nop 0
	v_pk_fma_f32 v[90:91], v[124:125], v[88:89], v[90:91] op_sel_hi:[0,1,1] neg_lo:[1,0,0] neg_hi:[1,0,0]
	flat_store_dwordx2 v[96:97], v[90:91]
.LBB0_801:
	s_or_b64 exec, exec, s[30:31]
	v_pk_mul_f32 v[90:91], v[80:81], v[88:89] op_sel_hi:[1,0]
	v_pk_mul_f32 v[80:81], v[80:81], v[88:89] op_sel:[0,1]
	v_pk_fma_f32 v[90:91], v[76:77], v[122:123], v[90:91] op_sel_hi:[1,0,1] neg_lo:[0,0,1] neg_hi:[0,0,1]
	v_pk_fma_f32 v[76:77], v[76:77], v[122:123], v[80:81] op_sel:[0,1,0] neg_lo:[0,0,1] neg_hi:[0,0,1]
	v_pk_fma_f32 v[128:129], v[64:65], v[128:129], v[90:91]
	v_pk_fma_f32 v[138:139], v[64:65], v[138:139], v[76:77]
	v_pk_mul_f32 v[64:65], v[82:83], v[88:89] op_sel_hi:[1,0]
	v_pk_mul_f32 v[76:77], v[82:83], v[88:89] op_sel:[0,1]
	v_pk_fma_f32 v[64:65], v[78:79], v[122:123], v[64:65] op_sel_hi:[1,0,1] neg_lo:[0,0,1] neg_hi:[0,0,1]
	v_pk_fma_f32 v[76:77], v[78:79], v[122:123], v[76:77] op_sel:[0,1,0] neg_lo:[0,0,1] neg_hi:[0,0,1]
	v_pk_fma_f32 v[136:137], v[66:67], v[136:137], v[64:65]
	v_pk_mul_f32 v[64:65], v[56:57], v[88:89] op_sel_hi:[1,0]
	v_pk_mul_f32 v[56:57], v[56:57], v[88:89] op_sel:[0,1]
	v_pk_fma_f32 v[140:141], v[66:67], v[140:141], v[76:77]
	v_pk_fma_f32 v[64:65], v[48:49], v[122:123], v[64:65] op_sel_hi:[1,0,1] neg_lo:[0,0,1] neg_hi:[0,0,1]
	v_pk_fma_f32 v[48:49], v[48:49], v[122:123], v[56:57] op_sel:[0,1,0] neg_lo:[0,0,1] neg_hi:[0,0,1]
	v_pk_fma_f32 v[142:143], v[44:45], v[142:143], v[64:65]
	v_pk_fma_f32 v[144:145], v[44:45], v[144:145], v[48:49]
	v_pk_mul_f32 v[44:45], v[58:59], v[88:89] op_sel_hi:[1,0]
	v_pk_mul_f32 v[48:49], v[58:59], v[88:89] op_sel:[0,1]
	s_waitcnt lgkmcnt(0)
	v_pk_mul_f32 v[148:149], v[118:119], v[136:137]
	v_pk_mul_f32 v[118:119], v[118:119], v[140:141]
	v_pk_fma_f32 v[44:45], v[50:51], v[122:123], v[44:45] op_sel_hi:[1,0,1] neg_lo:[0,0,1] neg_hi:[0,0,1]
	v_pk_fma_f32 v[48:49], v[50:51], v[122:123], v[48:49] op_sel:[0,1,0] neg_lo:[0,0,1] neg_hi:[0,0,1]
	v_pk_fma_f32 v[148:149], v[116:117], v[128:129], v[148:149]
	v_pk_fma_f32 v[116:117], v[116:117], v[138:139], v[118:119]
	v_pk_mul_f32 v[118:119], v[110:111], v[136:137]
	v_pk_mul_f32 v[110:111], v[110:111], v[140:141]
	v_pk_fma_f32 v[130:131], v[46:47], v[130:131], v[44:45]
	v_pk_fma_f32 v[146:147], v[46:47], v[146:147], v[48:49]
	v_pk_fma_f32 v[118:119], v[108:109], v[128:129], v[118:119]
	v_pk_fma_f32 v[108:109], v[108:109], v[138:139], v[110:111]
	v_pk_fma_f32 v[110:111], v[92:93], v[142:143], v[148:149]
	v_pk_fma_f32 v[92:93], v[92:93], v[144:145], v[116:117]
	ds_read_b128 v[88:91], v163 offset:20400
	ds_read_b128 v[64:67], v163 offset:20640
	ds_read_b128 v[44:47], v163 offset:20656
	ds_read_b128 v[76:79], v163 offset:20896
	ds_read_b128 v[48:51], v163 offset:20912
	ds_read_b128 v[80:83], v163 offset:21152
	ds_read_b128 v[56:59], v163 offset:21168
	ds_read_b128 v[104:107], v163 offset:21408
	ds_read_b128 v[96:99], v163 offset:21424
	ds_read_b64 v[122:123], v164 offset:21664
	ds_read_b128 v[112:115], v163 offset:20384
	ds_read_b64 v[124:125], v162 offset:21920
	v_pk_fma_f32 v[116:117], v[100:101], v[142:143], v[118:119]
	v_pk_fma_f32 v[100:101], v[100:101], v[144:145], v[108:109]
	v_pk_fma_f32 v[108:109], v[94:95], v[130:131], v[110:111]
	v_pk_fma_f32 v[92:93], v[94:95], v[146:147], v[92:93]
	v_pk_fma_f32 v[94:95], v[102:103], v[130:131], v[116:117]
	v_pk_fma_f32 v[100:101], v[102:103], v[146:147], v[100:101]
	v_add_f32_e32 v93, v92, v93
	v_add_f32_e32 v92, v108, v109
	s_nop 1
	v_add_f32_dpp v92, v92, v92 quad_perm:[1,0,3,2] row_mask:0xf bank_mask:0xf bound_ctrl:1
	v_add_f32_dpp v93, v93, v93 quad_perm:[1,0,3,2] row_mask:0xf bank_mask:0xf bound_ctrl:1
	s_nop 1
	v_add_f32_e32 v94, v94, v95
	v_add_f32_e32 v95, v100, v101
	v_add_f32_dpp v92, v92, v92 quad_perm:[2,3,0,1] row_mask:0xf bank_mask:0xf bound_ctrl:1
	v_add_f32_dpp v93, v93, v93 quad_perm:[2,3,0,1] row_mask:0xf bank_mask:0xf bound_ctrl:1
	v_add_f32_dpp v94, v94, v94 quad_perm:[1,0,3,2] row_mask:0xf bank_mask:0xf bound_ctrl:1
	v_add_f32_dpp v95, v95, v95 quad_perm:[1,0,3,2] row_mask:0xf bank_mask:0xf bound_ctrl:1
	v_add_f32_dpp v92, v92, v92 row_half_mirror row_mask:0xf bank_mask:0xf bound_ctrl:1
	v_add_f32_dpp v93, v93, v93 row_half_mirror row_mask:0xf bank_mask:0xf bound_ctrl:1
	v_add_f32_dpp v94, v94, v94 quad_perm:[2,3,0,1] row_mask:0xf bank_mask:0xf bound_ctrl:1
	v_add_f32_dpp v95, v95, v95 quad_perm:[2,3,0,1] row_mask:0xf bank_mask:0xf bound_ctrl:1
	s_nop 0
	v_mov_b32_dpp v100, v94 row_half_mirror row_mask:0xf bank_mask:0xf bound_ctrl:1
	v_mov_b32_dpp v101, v95 row_half_mirror row_mask:0xf bank_mask:0xf bound_ctrl:1
	s_and_saveexec_b64 s[30:31], s[8:9]
	s_cbranch_execz .LBB0_803
	v_pk_add_f32 v[94:95], v[94:95], v[100:101]
	v_lshl_add_u64 v[100:101], v[134:135], 0, s[48:49]
	v_pk_fma_f32 v[94:95], v[120:121], v[126:127], v[94:95] op_sel:[0,1,0]
	s_nop 0
	v_pk_fma_f32 v[94:95], v[126:127], v[92:93], v[94:95] op_sel_hi:[0,1,1] neg_lo:[1,0,0] neg_hi:[1,0,0]
	flat_store_dwordx2 v[100:101], v[94:95]
.LBB0_803:
	s_or_b64 exec, exec, s[30:31]
	v_pk_mul_f32 v[94:95], v[84:85], v[92:93] op_sel_hi:[1,0]
	v_pk_mul_f32 v[84:85], v[84:85], v[92:93] op_sel:[0,1]
	v_pk_fma_f32 v[94:95], v[72:73], v[120:121], v[94:95] op_sel_hi:[1,0,1] neg_lo:[0,0,1] neg_hi:[0,0,1]
	v_pk_fma_f32 v[72:73], v[72:73], v[120:121], v[84:85] op_sel:[0,1,0] neg_lo:[0,0,1] neg_hi:[0,0,1]
	v_pk_fma_f32 v[128:129], v[68:69], v[128:129], v[94:95]
	v_pk_fma_f32 v[138:139], v[68:69], v[138:139], v[72:73]
	v_pk_mul_f32 v[68:69], v[86:87], v[92:93] op_sel_hi:[1,0]
	v_pk_mul_f32 v[72:73], v[86:87], v[92:93] op_sel:[0,1]
	v_pk_fma_f32 v[68:69], v[74:75], v[120:121], v[68:69] op_sel_hi:[1,0,1] neg_lo:[0,0,1] neg_hi:[0,0,1]
	v_pk_fma_f32 v[72:73], v[74:75], v[120:121], v[72:73] op_sel:[0,1,0] neg_lo:[0,0,1] neg_hi:[0,0,1]
	v_pk_fma_f32 v[136:137], v[70:71], v[136:137], v[68:69]
	v_pk_mul_f32 v[68:69], v[60:61], v[92:93] op_sel_hi:[1,0]
	v_pk_mul_f32 v[60:61], v[60:61], v[92:93] op_sel:[0,1]
	v_pk_fma_f32 v[140:141], v[70:71], v[140:141], v[72:73]
	v_pk_fma_f32 v[68:69], v[52:53], v[120:121], v[68:69] op_sel_hi:[1,0,1] neg_lo:[0,0,1] neg_hi:[0,0,1]
	v_pk_fma_f32 v[52:53], v[52:53], v[120:121], v[60:61] op_sel:[0,1,0] neg_lo:[0,0,1] neg_hi:[0,0,1]
	v_pk_fma_f32 v[142:143], v[40:41], v[142:143], v[68:69]
	v_pk_fma_f32 v[144:145], v[40:41], v[144:145], v[52:53]
	v_pk_mul_f32 v[40:41], v[62:63], v[92:93] op_sel_hi:[1,0]
	v_pk_mul_f32 v[52:53], v[62:63], v[92:93] op_sel:[0,1]
	s_waitcnt lgkmcnt(0)
	v_pk_mul_f32 v[148:149], v[114:115], v[136:137]
	v_pk_mul_f32 v[114:115], v[114:115], v[140:141]
	v_pk_fma_f32 v[40:41], v[54:55], v[120:121], v[40:41] op_sel_hi:[1,0,1] neg_lo:[0,0,1] neg_hi:[0,0,1]
	v_pk_fma_f32 v[52:53], v[54:55], v[120:121], v[52:53] op_sel:[0,1,0] neg_lo:[0,0,1] neg_hi:[0,0,1]
	v_pk_fma_f32 v[148:149], v[112:113], v[128:129], v[148:149]
	v_pk_fma_f32 v[112:113], v[112:113], v[138:139], v[114:115]
	v_pk_mul_f32 v[114:115], v[106:107], v[136:137]
	v_pk_mul_f32 v[106:107], v[106:107], v[140:141]
	v_pk_fma_f32 v[130:131], v[42:43], v[130:131], v[40:41]
	v_pk_fma_f32 v[146:147], v[42:43], v[146:147], v[52:53]
	v_pk_fma_f32 v[114:115], v[104:105], v[128:129], v[114:115]
	v_pk_fma_f32 v[104:105], v[104:105], v[138:139], v[106:107]
	v_pk_fma_f32 v[106:107], v[88:89], v[142:143], v[148:149]
	v_pk_fma_f32 v[88:89], v[88:89], v[144:145], v[112:113]
	ds_read_b128 v[92:95], v163 offset:21968
	ds_read_b128 v[68:71], v163 offset:22208
	ds_read_b128 v[40:43], v163 offset:22224
	ds_read_b128 v[72:75], v163 offset:22464
	ds_read_b128 v[52:55], v163 offset:22480
	ds_read_b128 v[84:87], v163 offset:22720
	ds_read_b128 v[60:63], v163 offset:22736
	ds_read_b128 v[108:111], v163 offset:22976
	ds_read_b128 v[100:103], v163 offset:22992
	ds_read_b64 v[120:121], v164 offset:23232
	ds_read_b128 v[116:119], v163 offset:21952
	ds_read_b64 v[126:127], v162 offset:23488
	v_pk_fma_f32 v[112:113], v[96:97], v[142:143], v[114:115]
	v_pk_fma_f32 v[96:97], v[96:97], v[144:145], v[104:105]
	v_pk_fma_f32 v[104:105], v[90:91], v[130:131], v[106:107]
	v_pk_fma_f32 v[88:89], v[90:91], v[146:147], v[88:89]
	v_pk_fma_f32 v[90:91], v[98:99], v[130:131], v[112:113]
	v_pk_fma_f32 v[96:97], v[98:99], v[146:147], v[96:97]
	v_add_f32_e32 v89, v88, v89
	v_add_f32_e32 v88, v104, v105
	s_nop 1
	v_add_f32_dpp v88, v88, v88 quad_perm:[1,0,3,2] row_mask:0xf bank_mask:0xf bound_ctrl:1
	v_add_f32_dpp v89, v89, v89 quad_perm:[1,0,3,2] row_mask:0xf bank_mask:0xf bound_ctrl:1
	s_nop 1
	v_add_f32_e32 v90, v90, v91
	v_add_f32_e32 v91, v96, v97
	v_add_f32_dpp v88, v88, v88 quad_perm:[2,3,0,1] row_mask:0xf bank_mask:0xf bound_ctrl:1
	v_add_f32_dpp v89, v89, v89 quad_perm:[2,3,0,1] row_mask:0xf bank_mask:0xf bound_ctrl:1
	v_add_f32_dpp v90, v90, v90 quad_perm:[1,0,3,2] row_mask:0xf bank_mask:0xf bound_ctrl:1
	v_add_f32_dpp v91, v91, v91 quad_perm:[1,0,3,2] row_mask:0xf bank_mask:0xf bound_ctrl:1
	v_add_f32_dpp v88, v88, v88 row_half_mirror row_mask:0xf bank_mask:0xf bound_ctrl:1
	v_add_f32_dpp v89, v89, v89 row_half_mirror row_mask:0xf bank_mask:0xf bound_ctrl:1
	v_add_f32_dpp v90, v90, v90 quad_perm:[2,3,0,1] row_mask:0xf bank_mask:0xf bound_ctrl:1
	v_add_f32_dpp v91, v91, v91 quad_perm:[2,3,0,1] row_mask:0xf bank_mask:0xf bound_ctrl:1
	s_nop 0
	v_mov_b32_dpp v96, v90 row_half_mirror row_mask:0xf bank_mask:0xf bound_ctrl:1
	v_mov_b32_dpp v97, v91 row_half_mirror row_mask:0xf bank_mask:0xf bound_ctrl:1
	s_and_saveexec_b64 s[30:31], s[8:9]
	s_cbranch_execz .LBB0_805
	v_pk_add_f32 v[90:91], v[90:91], v[96:97]
	v_lshl_add_u64 v[96:97], v[134:135], 0, s[50:51]
	v_pk_fma_f32 v[90:91], v[122:123], v[124:125], v[90:91] op_sel:[0,1,0]
	s_nop 0
	v_pk_fma_f32 v[90:91], v[124:125], v[88:89], v[90:91] op_sel_hi:[0,1,1] neg_lo:[1,0,0] neg_hi:[1,0,0]
	flat_store_dwordx2 v[96:97], v[90:91]
.LBB0_805:
	s_or_b64 exec, exec, s[30:31]
	v_pk_mul_f32 v[90:91], v[80:81], v[88:89] op_sel_hi:[1,0]
	v_pk_mul_f32 v[80:81], v[80:81], v[88:89] op_sel:[0,1]
	v_pk_fma_f32 v[90:91], v[76:77], v[122:123], v[90:91] op_sel_hi:[1,0,1] neg_lo:[0,0,1] neg_hi:[0,0,1]
	v_pk_fma_f32 v[76:77], v[76:77], v[122:123], v[80:81] op_sel:[0,1,0] neg_lo:[0,0,1] neg_hi:[0,0,1]
	v_pk_fma_f32 v[128:129], v[64:65], v[128:129], v[90:91]
	v_pk_fma_f32 v[138:139], v[64:65], v[138:139], v[76:77]
	v_pk_mul_f32 v[64:65], v[82:83], v[88:89] op_sel_hi:[1,0]
	v_pk_mul_f32 v[76:77], v[82:83], v[88:89] op_sel:[0,1]
	v_pk_fma_f32 v[64:65], v[78:79], v[122:123], v[64:65] op_sel_hi:[1,0,1] neg_lo:[0,0,1] neg_hi:[0,0,1]
	v_pk_fma_f32 v[76:77], v[78:79], v[122:123], v[76:77] op_sel:[0,1,0] neg_lo:[0,0,1] neg_hi:[0,0,1]
	v_pk_fma_f32 v[136:137], v[66:67], v[136:137], v[64:65]
	v_pk_mul_f32 v[64:65], v[56:57], v[88:89] op_sel_hi:[1,0]
	v_pk_mul_f32 v[56:57], v[56:57], v[88:89] op_sel:[0,1]
	v_pk_fma_f32 v[140:141], v[66:67], v[140:141], v[76:77]
	v_pk_fma_f32 v[64:65], v[48:49], v[122:123], v[64:65] op_sel_hi:[1,0,1] neg_lo:[0,0,1] neg_hi:[0,0,1]
	v_pk_fma_f32 v[48:49], v[48:49], v[122:123], v[56:57] op_sel:[0,1,0] neg_lo:[0,0,1] neg_hi:[0,0,1]
	v_pk_fma_f32 v[142:143], v[44:45], v[142:143], v[64:65]
	v_pk_fma_f32 v[144:145], v[44:45], v[144:145], v[48:49]
	v_pk_mul_f32 v[44:45], v[58:59], v[88:89] op_sel_hi:[1,0]
	v_pk_mul_f32 v[48:49], v[58:59], v[88:89] op_sel:[0,1]
	s_waitcnt lgkmcnt(0)
	v_pk_mul_f32 v[148:149], v[118:119], v[136:137]
	v_pk_mul_f32 v[118:119], v[118:119], v[140:141]
	v_pk_fma_f32 v[44:45], v[50:51], v[122:123], v[44:45] op_sel_hi:[1,0,1] neg_lo:[0,0,1] neg_hi:[0,0,1]
	v_pk_fma_f32 v[48:49], v[50:51], v[122:123], v[48:49] op_sel:[0,1,0] neg_lo:[0,0,1] neg_hi:[0,0,1]
	v_pk_fma_f32 v[148:149], v[116:117], v[128:129], v[148:149]
	v_pk_fma_f32 v[116:117], v[116:117], v[138:139], v[118:119]
	v_pk_mul_f32 v[118:119], v[110:111], v[136:137]
	v_pk_mul_f32 v[110:111], v[110:111], v[140:141]
	v_pk_fma_f32 v[130:131], v[46:47], v[130:131], v[44:45]
	v_pk_fma_f32 v[146:147], v[46:47], v[146:147], v[48:49]
	v_pk_fma_f32 v[118:119], v[108:109], v[128:129], v[118:119]
	v_pk_fma_f32 v[108:109], v[108:109], v[138:139], v[110:111]
	v_pk_fma_f32 v[110:111], v[92:93], v[142:143], v[148:149]
	v_pk_fma_f32 v[92:93], v[92:93], v[144:145], v[116:117]
	ds_read_b128 v[88:91], v163 offset:23536
	ds_read_b128 v[48:51], v163 offset:23776
	ds_read_b128 v[56:59], v163 offset:23792
	ds_read_b128 v[76:79], v163 offset:24032
	ds_read_b128 v[44:47], v163 offset:24048
	ds_read_b128 v[80:83], v163 offset:24288
	ds_read_b128 v[64:67], v163 offset:24304
	ds_read_b128 v[104:107], v163 offset:24544
	ds_read_b128 v[96:99], v163 offset:24560
	ds_read_b64 v[122:123], v164 offset:24800
	ds_read_b128 v[112:115], v163 offset:23520
	ds_read_b64 v[124:125], v162 offset:25056
	v_pk_fma_f32 v[116:117], v[100:101], v[142:143], v[118:119]
	v_pk_fma_f32 v[100:101], v[100:101], v[144:145], v[108:109]
	v_pk_fma_f32 v[108:109], v[94:95], v[130:131], v[110:111]
	v_pk_fma_f32 v[92:93], v[94:95], v[146:147], v[92:93]
	v_pk_fma_f32 v[94:95], v[102:103], v[130:131], v[116:117]
	v_pk_fma_f32 v[100:101], v[102:103], v[146:147], v[100:101]
	v_add_f32_e32 v93, v92, v93
	v_add_f32_e32 v92, v108, v109
	s_nop 1
	v_add_f32_dpp v92, v92, v92 quad_perm:[1,0,3,2] row_mask:0xf bank_mask:0xf bound_ctrl:1
	v_add_f32_dpp v93, v93, v93 quad_perm:[1,0,3,2] row_mask:0xf bank_mask:0xf bound_ctrl:1
	s_nop 1
	v_add_f32_e32 v94, v94, v95
	v_add_f32_e32 v95, v100, v101
	v_add_f32_dpp v92, v92, v92 quad_perm:[2,3,0,1] row_mask:0xf bank_mask:0xf bound_ctrl:1
	v_add_f32_dpp v93, v93, v93 quad_perm:[2,3,0,1] row_mask:0xf bank_mask:0xf bound_ctrl:1
	v_add_f32_dpp v94, v94, v94 quad_perm:[1,0,3,2] row_mask:0xf bank_mask:0xf bound_ctrl:1
	v_add_f32_dpp v95, v95, v95 quad_perm:[1,0,3,2] row_mask:0xf bank_mask:0xf bound_ctrl:1
	v_add_f32_dpp v92, v92, v92 row_half_mirror row_mask:0xf bank_mask:0xf bound_ctrl:1
	v_add_f32_dpp v93, v93, v93 row_half_mirror row_mask:0xf bank_mask:0xf bound_ctrl:1
	v_add_f32_dpp v94, v94, v94 quad_perm:[2,3,0,1] row_mask:0xf bank_mask:0xf bound_ctrl:1
	v_add_f32_dpp v95, v95, v95 quad_perm:[2,3,0,1] row_mask:0xf bank_mask:0xf bound_ctrl:1
	s_nop 0
	v_mov_b32_dpp v100, v94 row_half_mirror row_mask:0xf bank_mask:0xf bound_ctrl:1
	v_mov_b32_dpp v101, v95 row_half_mirror row_mask:0xf bank_mask:0xf bound_ctrl:1
	s_and_saveexec_b64 s[30:31], s[8:9]
	s_cbranch_execz .LBB0_807
	v_pk_add_f32 v[94:95], v[94:95], v[100:101]
	v_lshl_add_u64 v[100:101], v[134:135], 0, s[52:53]
	v_pk_fma_f32 v[94:95], v[120:121], v[126:127], v[94:95] op_sel:[0,1,0]
	s_nop 0
	v_pk_fma_f32 v[94:95], v[126:127], v[92:93], v[94:95] op_sel_hi:[0,1,1] neg_lo:[1,0,0] neg_hi:[1,0,0]
	flat_store_dwordx2 v[100:101], v[94:95]

.LBB0_873:
	v_or_b32_e32 v56, s28, v158
	v_mad_u32_u24 v159, v56, s38, 0
	v_lshl_add_u32 v160, v151, 2, v159
	v_or_b32_e32 v56, s28, v157
	v_readlane_b32 s28, v253, 35
	ds_read_b128 v[120:123], v160
	ds_read_b128 v[128:131], v160 offset:16
	ds_read_b128 v[88:91], v160 offset:256
	ds_read_b128 v[64:67], v160 offset:272
	ds_read_b128 v[100:103], v160 offset:512
	ds_read_b128 v[76:79], v160 offset:528
	ds_read_b128 v[108:111], v160 offset:768
	ds_read_b128 v[84:87], v160 offset:784
	ds_read_b128 v[136:139], v160 offset:1024
	v_sub_u32_e32 v57, 0x7ff, v56
	v_readlane_b32 s29, v253, 36
	s_waitcnt lgkmcnt(0)
	v_pk_mul_f32 v[146:147], v[46:47], v[122:123]
	v_pk_mul_f32 v[122:123], v[54:55], v[122:123]
	v_cndmask_b32_e64 v56, v57, v56, s[28:29]
	v_add_u32_e32 v56, s35, v56
	v_ashrrev_i32_e32 v57, 31, v56
	v_lshlrev_b64 v[56:57], 12, v[56:57]
	v_lshl_add_u32 v161, v150, 2, v159
	v_pk_fma_f32 v[146:147], v[44:45], v[120:121], v[146:147]
	v_pk_fma_f32 v[120:121], v[52:53], v[120:121], v[122:123]
	v_pk_mul_f32 v[122:123], v[46:47], v[138:139]
	v_pk_mul_f32 v[138:139], v[54:55], v[138:139]
	v_lshl_add_u64 v[134:135], v[132:133], 0, v[56:57]
	v_add_u32_e32 v56, 0x400, v161
	v_pk_fma_f32 v[122:123], v[44:45], v[136:137], v[122:123]
	v_pk_fma_f32 v[136:137], v[52:53], v[136:137], v[138:139]
	v_pk_fma_f32 v[138:139], v[40:41], v[128:129], v[146:147]
	v_pk_fma_f32 v[120:121], v[48:49], v[128:129], v[120:121]
	ds_read2_b64 v[56:59], v56 offset0:32 offset1:228
	ds_read_b128 v[142:145], v160 offset:1040
	ds_read_b128 v[116:119], v160 offset:1568
	ds_read_b128 v[104:107], v160 offset:1584
	ds_read_b128 v[80:83], v160 offset:1824
	ds_read_b128 v[60:63], v160 offset:1840
	ds_read_b128 v[92:95], v160 offset:2080
	ds_read_b128 v[68:71], v160 offset:2096
	ds_read_b128 v[96:99], v160 offset:2336
	ds_read_b128 v[72:75], v160 offset:2352
	ds_read_b128 v[124:127], v160 offset:2592
	ds_read_b128 v[112:115], v160 offset:2608
	ds_read_b64 v[140:141], v159 offset:3104
	s_waitcnt lgkmcnt(0)
	v_pk_fma_f32 v[128:129], v[48:49], v[142:143], v[136:137]
	v_pk_fma_f32 v[136:137], v[42:43], v[130:131], v[138:139]
	v_pk_fma_f32 v[120:121], v[50:51], v[130:131], v[120:121]
	v_add_f32_e32 v121, v120, v121
	v_add_f32_e32 v120, v136, v137
	v_pk_fma_f32 v[122:123], v[40:41], v[142:143], v[122:123]
	v_pk_fma_f32 v[128:129], v[50:51], v[144:145], v[128:129]
	v_add_f32_dpp v120, v120, v120 quad_perm:[1,0,3,2] row_mask:0xf bank_mask:0xf bound_ctrl:1
	v_add_f32_dpp v121, v121, v121 quad_perm:[1,0,3,2] row_mask:0xf bank_mask:0xf bound_ctrl:1
	v_pk_fma_f32 v[122:123], v[42:43], v[144:145], v[122:123]
	v_add_f32_e32 v122, v122, v123
	v_add_f32_e32 v123, v128, v129
	v_add_f32_dpp v120, v120, v120 quad_perm:[2,3,0,1] row_mask:0xf bank_mask:0xf bound_ctrl:1
	v_add_f32_dpp v121, v121, v121 quad_perm:[2,3,0,1] row_mask:0xf bank_mask:0xf bound_ctrl:1
	v_add_f32_dpp v122, v122, v122 quad_perm:[1,0,3,2] row_mask:0xf bank_mask:0xf bound_ctrl:1
	v_add_f32_dpp v123, v123, v123 quad_perm:[1,0,3,2] row_mask:0xf bank_mask:0xf bound_ctrl:1
	v_add_f32_dpp v120, v120, v120 row_half_mirror row_mask:0xf bank_mask:0xf bound_ctrl:1
	v_add_f32_dpp v121, v121, v121 row_half_mirror row_mask:0xf bank_mask:0xf bound_ctrl:1
	v_add_f32_dpp v122, v122, v122 quad_perm:[2,3,0,1] row_mask:0xf bank_mask:0xf bound_ctrl:1
	v_add_f32_dpp v123, v123, v123 quad_perm:[2,3,0,1] row_mask:0xf bank_mask:0xf bound_ctrl:1
	s_nop 0
	v_mov_b32_dpp v128, v122 row_half_mirror row_mask:0xf bank_mask:0xf bound_ctrl:1
	v_mov_b32_dpp v129, v123 row_half_mirror row_mask:0xf bank_mask:0xf bound_ctrl:1
	s_and_saveexec_b64 s[28:29], s[8:9]
	s_cbranch_execz .LBB0_875
	ds_read_b64 v[130:131], v159 offset:1536
	v_pk_add_f32 v[122:123], v[122:123], v[128:129]
	s_waitcnt lgkmcnt(0)
	v_pk_fma_f32 v[122:123], v[56:57], v[130:131], v[122:123] op_sel:[0,1,0]
	s_nop 0
	v_pk_fma_f32 v[122:123], v[120:121], v[130:131], v[122:123] op_sel_hi:[1,0,1] neg_lo:[1,0,0] neg_hi:[1,0,0]
	flat_store_dwordx2 v[134:135], v[122:123]
.LBB0_875:
	s_or_b64 exec, exec, s[28:29]
	v_pk_mul_f32 v[122:123], v[108:109], v[120:121] op_sel_hi:[1,0]
	v_pk_mul_f32 v[108:109], v[108:109], v[120:121] op_sel:[0,1]
	v_pk_fma_f32 v[122:123], v[100:101], v[56:57], v[122:123] op_sel_hi:[1,0,1] neg_lo:[0,0,1] neg_hi:[0,0,1]
	v_pk_fma_f32 v[100:101], v[100:101], v[56:57], v[108:109] op_sel:[0,1,0] neg_lo:[0,0,1] neg_hi:[0,0,1]
	v_pk_fma_f32 v[44:45], v[44:45], v[88:89], v[122:123]
	v_pk_fma_f32 v[52:53], v[52:53], v[88:89], v[100:101]
	v_pk_mul_f32 v[88:89], v[110:111], v[120:121] op_sel_hi:[1,0]
	v_pk_mul_f32 v[100:101], v[110:111], v[120:121] op_sel:[0,1]
	v_pk_fma_f32 v[88:89], v[102:103], v[56:57], v[88:89] op_sel_hi:[1,0,1] neg_lo:[0,0,1] neg_hi:[0,0,1]
	v_pk_fma_f32 v[100:101], v[102:103], v[56:57], v[100:101] op_sel:[0,1,0] neg_lo:[0,0,1] neg_hi:[0,0,1]
	v_pk_fma_f32 v[46:47], v[46:47], v[90:91], v[88:89]
	v_pk_mul_f32 v[88:89], v[84:85], v[120:121] op_sel_hi:[1,0]
	v_pk_mul_f32 v[84:85], v[84:85], v[120:121] op_sel:[0,1]
	v_pk_fma_f32 v[54:55], v[54:55], v[90:91], v[100:101]
	v_pk_fma_f32 v[88:89], v[76:77], v[56:57], v[88:89] op_sel_hi:[1,0,1] neg_lo:[0,0,1] neg_hi:[0,0,1]
	v_pk_fma_f32 v[76:77], v[76:77], v[56:57], v[84:85] op_sel:[0,1,0] neg_lo:[0,0,1] neg_hi:[0,0,1]
	v_pk_fma_f32 v[142:143], v[40:41], v[64:65], v[88:89]
	v_pk_fma_f32 v[144:145], v[48:49], v[64:65], v[76:77]
	v_pk_mul_f32 v[40:41], v[86:87], v[120:121] op_sel_hi:[1,0]
	v_pk_mul_f32 v[48:49], v[86:87], v[120:121] op_sel:[0,1]
	s_waitcnt lgkmcnt(0)
	v_pk_mul_f32 v[148:149], v[118:119], v[46:47]
	v_pk_mul_f32 v[118:119], v[118:119], v[54:55]
	v_pk_fma_f32 v[40:41], v[78:79], v[56:57], v[40:41] op_sel_hi:[1,0,1] neg_lo:[0,0,1] neg_hi:[0,0,1]
	v_pk_fma_f32 v[48:49], v[78:79], v[56:57], v[48:49] op_sel:[0,1,0] neg_lo:[0,0,1] neg_hi:[0,0,1]
	v_pk_fma_f32 v[148:149], v[116:117], v[44:45], v[148:149]
	v_pk_fma_f32 v[116:117], v[116:117], v[52:53], v[118:119]
	v_pk_mul_f32 v[118:119], v[126:127], v[46:47]
	v_pk_mul_f32 v[126:127], v[126:127], v[54:55]
	v_pk_fma_f32 v[56:57], v[42:43], v[66:67], v[40:41]
	v_pk_fma_f32 v[146:147], v[50:51], v[66:67], v[48:49]
	v_pk_fma_f32 v[118:119], v[124:125], v[44:45], v[118:119]
	v_pk_fma_f32 v[124:125], v[124:125], v[52:53], v[126:127]
	v_pk_fma_f32 v[126:127], v[104:105], v[142:143], v[148:149]
	v_pk_fma_f32 v[104:105], v[104:105], v[144:145], v[116:117]
	ds_read_b128 v[100:103], v160 offset:3152
	ds_read_b128 v[76:79], v160 offset:3392
	ds_read_b128 v[40:43], v160 offset:3408
	ds_read_b128 v[84:87], v160 offset:3648
	ds_read_b128 v[48:51], v160 offset:3664
	ds_read_b128 v[88:91], v160 offset:3904
	ds_read_b128 v[64:67], v160 offset:3920
	ds_read_b128 v[120:123], v160 offset:4160
	ds_read_b128 v[108:111], v160 offset:4176
	ds_read_b64 v[136:137], v161 offset:4416
	ds_read_b128 v[128:131], v160 offset:3136
	ds_read_b64 v[138:139], v159 offset:4672
	v_pk_fma_f32 v[116:117], v[112:113], v[142:143], v[118:119]
	v_pk_fma_f32 v[112:113], v[112:113], v[144:145], v[124:125]
	v_pk_fma_f32 v[118:119], v[106:107], v[56:57], v[126:127]
	v_pk_fma_f32 v[104:105], v[106:107], v[146:147], v[104:105]
	v_pk_fma_f32 v[106:107], v[114:115], v[56:57], v[116:117]
	v_pk_fma_f32 v[112:113], v[114:115], v[146:147], v[112:113]
	v_add_f32_e32 v105, v104, v105
	v_add_f32_e32 v104, v118, v119
	s_nop 1
	v_add_f32_dpp v104, v104, v104 quad_perm:[1,0,3,2] row_mask:0xf bank_mask:0xf bound_ctrl:1
	v_add_f32_dpp v105, v105, v105 quad_perm:[1,0,3,2] row_mask:0xf bank_mask:0xf bound_ctrl:1
	s_nop 1
	v_add_f32_e32 v106, v106, v107
	v_add_f32_e32 v107, v112, v113
	v_add_f32_dpp v104, v104, v104 quad_perm:[2,3,0,1] row_mask:0xf bank_mask:0xf bound_ctrl:1
	v_add_f32_dpp v105, v105, v105 quad_perm:[2,3,0,1] row_mask:0xf bank_mask:0xf bound_ctrl:1
	v_add_f32_dpp v106, v106, v106 quad_perm:[1,0,3,2] row_mask:0xf bank_mask:0xf bound_ctrl:1
	v_add_f32_dpp v107, v107, v107 quad_perm:[1,0,3,2] row_mask:0xf bank_mask:0xf bound_ctrl:1
	v_add_f32_dpp v104, v104, v104 row_half_mirror row_mask:0xf bank_mask:0xf bound_ctrl:1
	v_add_f32_dpp v105, v105, v105 row_half_mirror row_mask:0xf bank_mask:0xf bound_ctrl:1
	v_add_f32_dpp v106, v106, v106 quad_perm:[2,3,0,1] row_mask:0xf bank_mask:0xf bound_ctrl:1
	v_add_f32_dpp v107, v107, v107 quad_perm:[2,3,0,1] row_mask:0xf bank_mask:0xf bound_ctrl:1
	s_nop 0
	v_mov_b32_dpp v112, v106 row_half_mirror row_mask:0xf bank_mask:0xf bound_ctrl:1
	v_mov_b32_dpp v113, v107 row_half_mirror row_mask:0xf bank_mask:0xf bound_ctrl:1
	s_and_saveexec_b64 s[28:29], s[8:9]
	s_cbranch_execz .LBB0_877
	v_pk_add_f32 v[106:107], v[106:107], v[112:113]
	v_readlane_b32 s30, v254, 19
	v_pk_fma_f32 v[106:107], v[58:59], v[140:141], v[106:107] op_sel:[0,1,0]
	v_readlane_b32 s31, v254, 20
	v_pk_fma_f32 v[106:107], v[140:141], v[104:105], v[106:107] op_sel_hi:[0,1,1] neg_lo:[1,0,0] neg_hi:[1,0,0]
	s_nop 0
	v_lshl_add_u64 v[112:113], s[30:31], 2, v[134:135]
	flat_store_dwordx2 v[112:113], v[106:107]
.LBB0_877:
	s_or_b64 exec, exec, s[28:29]
	v_pk_mul_f32 v[106:107], v[96:97], v[104:105] op_sel_hi:[1,0]
	v_pk_mul_f32 v[96:97], v[96:97], v[104:105] op_sel:[0,1]
	v_pk_fma_f32 v[106:107], v[92:93], v[58:59], v[106:107] op_sel_hi:[1,0,1] neg_lo:[0,0,1] neg_hi:[0,0,1]
	v_pk_fma_f32 v[92:93], v[92:93], v[58:59], v[96:97] op_sel:[0,1,0] neg_lo:[0,0,1] neg_hi:[0,0,1]
	v_pk_fma_f32 v[116:117], v[80:81], v[44:45], v[106:107]
	v_pk_mul_f32 v[44:45], v[98:99], v[104:105] op_sel_hi:[1,0]
	v_pk_fma_f32 v[118:119], v[80:81], v[52:53], v[92:93]
	v_pk_fma_f32 v[44:45], v[94:95], v[58:59], v[44:45] op_sel_hi:[1,0,1] neg_lo:[0,0,1] neg_hi:[0,0,1]
	v_pk_mul_f32 v[52:53], v[98:99], v[104:105] op_sel:[0,1]
	v_pk_fma_f32 v[140:141], v[82:83], v[46:47], v[44:45]
	v_pk_mul_f32 v[44:45], v[72:73], v[104:105] op_sel_hi:[1,0]
	v_pk_mul_f32 v[46:47], v[72:73], v[104:105] op_sel:[0,1]
	v_pk_fma_f32 v[44:45], v[68:69], v[58:59], v[44:45] op_sel_hi:[1,0,1] neg_lo:[0,0,1] neg_hi:[0,0,1]
	v_pk_fma_f32 v[46:47], v[68:69], v[58:59], v[46:47] op_sel:[0,1,0] neg_lo:[0,0,1] neg_hi:[0,0,1]
	v_pk_fma_f32 v[52:53], v[94:95], v[58:59], v[52:53] op_sel:[0,1,0] neg_lo:[0,0,1] neg_hi:[0,0,1]
	v_pk_fma_f32 v[142:143], v[60:61], v[142:143], v[44:45]
	v_pk_fma_f32 v[60:61], v[60:61], v[144:145], v[46:47]
	v_pk_mul_f32 v[44:45], v[74:75], v[104:105] op_sel_hi:[1,0]
	v_pk_mul_f32 v[46:47], v[74:75], v[104:105] op_sel:[0,1]
	v_pk_fma_f32 v[148:149], v[82:83], v[54:55], v[52:53]
	v_pk_fma_f32 v[44:45], v[70:71], v[58:59], v[44:45] op_sel_hi:[1,0,1] neg_lo:[0,0,1] neg_hi:[0,0,1]
	v_pk_fma_f32 v[46:47], v[70:71], v[58:59], v[46:47] op_sel:[0,1,0] neg_lo:[0,0,1] neg_hi:[0,0,1]
	v_pk_fma_f32 v[144:145], v[62:63], v[56:57], v[44:45]
	v_pk_fma_f32 v[62:63], v[62:63], v[146:147], v[46:47]
	s_waitcnt lgkmcnt(0)
	v_pk_mul_f32 v[146:147], v[130:131], v[140:141]
	v_pk_mul_f32 v[130:131], v[130:131], v[148:149]
	v_pk_fma_f32 v[146:147], v[128:129], v[116:117], v[146:147]
	v_pk_fma_f32 v[128:129], v[128:129], v[118:119], v[130:131]
	v_pk_mul_f32 v[130:131], v[122:123], v[140:141]
	v_pk_mul_f32 v[122:123], v[122:123], v[148:149]
	v_pk_fma_f32 v[130:131], v[120:121], v[116:117], v[130:131]
	v_pk_fma_f32 v[120:121], v[120:121], v[118:119], v[122:123]
	v_pk_fma_f32 v[122:123], v[100:101], v[142:143], v[146:147]
	v_pk_fma_f32 v[100:101], v[100:101], v[60:61], v[128:129]
	ds_read_b128 v[92:95], v160 offset:4720
	ds_read_b128 v[68:71], v160 offset:4960
	ds_read_b128 v[44:47], v160 offset:4976
	ds_read_b128 v[72:75], v160 offset:5216
	ds_read_b128 v[52:55], v160 offset:5232
	ds_read_b128 v[80:83], v160 offset:5472
	ds_read_b128 v[56:59], v160 offset:5488
	ds_read_b128 v[104:107], v160 offset:5728
	ds_read_b128 v[96:99], v160 offset:5744
	ds_read_b64 v[124:125], v161 offset:5984
	ds_read_b128 v[112:115], v160 offset:4704
	ds_read_b64 v[126:127], v159 offset:6240
	v_pk_fma_f32 v[128:129], v[108:109], v[142:143], v[130:131]
	v_pk_fma_f32 v[108:109], v[108:109], v[60:61], v[120:121]
	v_pk_fma_f32 v[120:121], v[102:103], v[144:145], v[122:123]
	v_pk_fma_f32 v[100:101], v[102:103], v[62:63], v[100:101]
	v_pk_fma_f32 v[102:103], v[110:111], v[144:145], v[128:129]
	v_pk_fma_f32 v[108:109], v[110:111], v[62:63], v[108:109]
	v_add_f32_e32 v101, v100, v101
	v_add_f32_e32 v100, v120, v121
	s_nop 1
	v_add_f32_dpp v100, v100, v100 quad_perm:[1,0,3,2] row_mask:0xf bank_mask:0xf bound_ctrl:1
	v_add_f32_dpp v101, v101, v101 quad_perm:[1,0,3,2] row_mask:0xf bank_mask:0xf bound_ctrl:1
	s_nop 1
	v_add_f32_e32 v102, v102, v103
	v_add_f32_e32 v103, v108, v109
	v_add_f32_dpp v100, v100, v100 quad_perm:[2,3,0,1] row_mask:0xf bank_mask:0xf bound_ctrl:1
	v_add_f32_dpp v101, v101, v101 quad_perm:[2,3,0,1] row_mask:0xf bank_mask:0xf bound_ctrl:1
	v_add_f32_dpp v102, v102, v102 quad_perm:[1,0,3,2] row_mask:0xf bank_mask:0xf bound_ctrl:1
	v_add_f32_dpp v103, v103, v103 quad_perm:[1,0,3,2] row_mask:0xf bank_mask:0xf bound_ctrl:1
	v_add_f32_dpp v100, v100, v100 row_half_mirror row_mask:0xf bank_mask:0xf bound_ctrl:1
	v_add_f32_dpp v101, v101, v101 row_half_mirror row_mask:0xf bank_mask:0xf bound_ctrl:1
	v_add_f32_dpp v102, v102, v102 quad_perm:[2,3,0,1] row_mask:0xf bank_mask:0xf bound_ctrl:1
	v_add_f32_dpp v103, v103, v103 quad_perm:[2,3,0,1] row_mask:0xf bank_mask:0xf bound_ctrl:1
	s_nop 0
	v_mov_b32_dpp v108, v102 row_half_mirror row_mask:0xf bank_mask:0xf bound_ctrl:1
	v_mov_b32_dpp v109, v103 row_half_mirror row_mask:0xf bank_mask:0xf bound_ctrl:1
	s_and_saveexec_b64 s[28:29], s[8:9]
	s_cbranch_execz .LBB0_879
	v_pk_add_f32 v[102:103], v[102:103], v[108:109]
	v_readlane_b32 s30, v253, 38
	v_pk_fma_f32 v[102:103], v[136:137], v[138:139], v[102:103] op_sel:[0,1,0]
	v_readlane_b32 s31, v253, 39
	v_pk_fma_f32 v[102:103], v[138:139], v[100:101], v[102:103] op_sel_hi:[0,1,1] neg_lo:[1,0,0] neg_hi:[1,0,0]
	s_nop 0
	v_lshl_add_u64 v[108:109], v[134:135], 0, s[30:31]
	flat_store_dwordx2 v[108:109], v[102:103]
.LBB0_879:
	s_or_b64 exec, exec, s[28:29]
	v_pk_mul_f32 v[102:103], v[88:89], v[100:101] op_sel_hi:[1,0]
	v_pk_mul_f32 v[88:89], v[88:89], v[100:101] op_sel:[0,1]
	v_pk_fma_f32 v[102:103], v[84:85], v[136:137], v[102:103] op_sel_hi:[1,0,1] neg_lo:[0,0,1] neg_hi:[0,0,1]
	v_pk_fma_f32 v[84:85], v[84:85], v[136:137], v[88:89] op_sel:[0,1,0] neg_lo:[0,0,1] neg_hi:[0,0,1]
	v_pk_fma_f32 v[122:123], v[76:77], v[116:117], v[102:103]
	v_pk_fma_f32 v[130:131], v[76:77], v[118:119], v[84:85]
	v_pk_mul_f32 v[76:77], v[90:91], v[100:101] op_sel_hi:[1,0]
	v_pk_mul_f32 v[84:85], v[90:91], v[100:101] op_sel:[0,1]
	v_pk_fma_f32 v[76:77], v[86:87], v[136:137], v[76:77] op_sel_hi:[1,0,1] neg_lo:[0,0,1] neg_hi:[0,0,1]
	v_pk_fma_f32 v[84:85], v[86:87], v[136:137], v[84:85] op_sel:[0,1,0] neg_lo:[0,0,1] neg_hi:[0,0,1]
	v_pk_fma_f32 v[138:139], v[78:79], v[140:141], v[76:77]
	v_pk_mul_f32 v[76:77], v[64:65], v[100:101] op_sel_hi:[1,0]
	v_pk_mul_f32 v[64:65], v[64:65], v[100:101] op_sel:[0,1]
	v_pk_fma_f32 v[140:141], v[78:79], v[148:149], v[84:85]
	v_pk_fma_f32 v[76:77], v[48:49], v[136:137], v[76:77] op_sel_hi:[1,0,1] neg_lo:[0,0,1] neg_hi:[0,0,1]
	v_pk_fma_f32 v[48:49], v[48:49], v[136:137], v[64:65] op_sel:[0,1,0] neg_lo:[0,0,1] neg_hi:[0,0,1]
	v_pk_fma_f32 v[142:143], v[40:41], v[142:143], v[76:77]
	v_pk_fma_f32 v[146:147], v[40:41], v[60:61], v[48:49]
	v_pk_mul_f32 v[40:41], v[66:67], v[100:101] op_sel_hi:[1,0]
	v_pk_mul_f32 v[48:49], v[66:67], v[100:101] op_sel:[0,1]
	s_waitcnt lgkmcnt(0)
	v_pk_mul_f32 v[148:149], v[114:115], v[138:139]
	v_pk_mul_f32 v[114:115], v[114:115], v[140:141]
	v_pk_fma_f32 v[40:41], v[50:51], v[136:137], v[40:41] op_sel_hi:[1,0,1] neg_lo:[0,0,1] neg_hi:[0,0,1]
	v_pk_fma_f32 v[48:49], v[50:51], v[136:137], v[48:49] op_sel:[0,1,0] neg_lo:[0,0,1] neg_hi:[0,0,1]
	v_pk_fma_f32 v[148:149], v[112:113], v[122:123], v[148:149]
	v_pk_fma_f32 v[112:113], v[112:113], v[130:131], v[114:115]
	v_pk_mul_f32 v[114:115], v[106:107], v[138:139]
	v_pk_mul_f32 v[106:107], v[106:107], v[140:141]
	v_pk_fma_f32 v[136:137], v[42:43], v[144:145], v[40:41]
	v_pk_fma_f32 v[144:145], v[42:43], v[62:63], v[48:49]
	v_pk_fma_f32 v[114:115], v[104:105], v[122:123], v[114:115]
	v_pk_fma_f32 v[104:105], v[104:105], v[130:131], v[106:107]
	v_pk_fma_f32 v[106:107], v[92:93], v[142:143], v[148:149]
	v_pk_fma_f32 v[92:93], v[92:93], v[146:147], v[112:113]
	ds_read_b128 v[88:91], v160 offset:6288
	ds_read_b128 v[64:67], v160 offset:6528
	ds_read_b128 v[40:43], v160 offset:6544
	ds_read_b128 v[76:79], v160 offset:6784
	ds_read_b128 v[48:51], v160 offset:6800
	ds_read_b128 v[84:87], v160 offset:7040
	ds_read_b128 v[60:63], v160 offset:7056
	ds_read_b128 v[108:111], v160 offset:7296
	ds_read_b128 v[100:103], v160 offset:7312
	ds_read_b64 v[120:121], v161 offset:7552
	ds_read_b128 v[116:119], v160 offset:6272
	ds_read_b64 v[128:129], v159 offset:7808
	v_pk_fma_f32 v[112:113], v[96:97], v[142:143], v[114:115]
	v_pk_fma_f32 v[96:97], v[96:97], v[146:147], v[104:105]
	v_pk_fma_f32 v[104:105], v[94:95], v[136:137], v[106:107]
	v_pk_fma_f32 v[92:93], v[94:95], v[144:145], v[92:93]
	v_pk_fma_f32 v[94:95], v[98:99], v[136:137], v[112:113]
	v_pk_fma_f32 v[96:97], v[98:99], v[144:145], v[96:97]
	v_add_f32_e32 v93, v92, v93
	v_add_f32_e32 v92, v104, v105
	s_nop 1
	v_add_f32_dpp v92, v92, v92 quad_perm:[1,0,3,2] row_mask:0xf bank_mask:0xf bound_ctrl:1
	v_add_f32_dpp v93, v93, v93 quad_perm:[1,0,3,2] row_mask:0xf bank_mask:0xf bound_ctrl:1
	s_nop 1
	v_add_f32_e32 v94, v94, v95
	v_add_f32_e32 v95, v96, v97
	v_add_f32_dpp v92, v92, v92 quad_perm:[2,3,0,1] row_mask:0xf bank_mask:0xf bound_ctrl:1
	v_add_f32_dpp v93, v93, v93 quad_perm:[2,3,0,1] row_mask:0xf bank_mask:0xf bound_ctrl:1
	v_add_f32_dpp v94, v94, v94 quad_perm:[1,0,3,2] row_mask:0xf bank_mask:0xf bound_ctrl:1
	v_add_f32_dpp v95, v95, v95 quad_perm:[1,0,3,2] row_mask:0xf bank_mask:0xf bound_ctrl:1
	v_add_f32_dpp v92, v92, v92 row_half_mirror row_mask:0xf bank_mask:0xf bound_ctrl:1
	v_add_f32_dpp v93, v93, v93 row_half_mirror row_mask:0xf bank_mask:0xf bound_ctrl:1
	v_add_f32_dpp v94, v94, v94 quad_perm:[2,3,0,1] row_mask:0xf bank_mask:0xf bound_ctrl:1
	v_add_f32_dpp v95, v95, v95 quad_perm:[2,3,0,1] row_mask:0xf bank_mask:0xf bound_ctrl:1
	s_nop 0
	v_mov_b32_dpp v96, v94 row_half_mirror row_mask:0xf bank_mask:0xf bound_ctrl:1
	v_mov_b32_dpp v97, v95 row_half_mirror row_mask:0xf bank_mask:0xf bound_ctrl:1
	s_and_saveexec_b64 s[28:29], s[8:9]
	s_cbranch_execz .LBB0_881
	v_pk_add_f32 v[94:95], v[94:95], v[96:97]
	v_readlane_b32 s30, v253, 63
	v_pk_fma_f32 v[94:95], v[124:125], v[126:127], v[94:95] op_sel:[0,1,0]
	v_readlane_b32 s31, v254, 0
	v_pk_fma_f32 v[94:95], v[126:127], v[92:93], v[94:95] op_sel_hi:[0,1,1] neg_lo:[1,0,0] neg_hi:[1,0,0]
	s_nop 0
	v_lshl_add_u64 v[96:97], v[134:135], 0, s[30:31]
	flat_store_dwordx2 v[96:97], v[94:95]
.LBB0_881:
	s_or_b64 exec, exec, s[28:29]
	v_pk_mul_f32 v[94:95], v[80:81], v[92:93] op_sel_hi:[1,0]
	v_pk_mul_f32 v[80:81], v[80:81], v[92:93] op_sel:[0,1]
	v_pk_fma_f32 v[94:95], v[72:73], v[124:125], v[94:95] op_sel_hi:[1,0,1] neg_lo:[0,0,1] neg_hi:[0,0,1]
	v_pk_fma_f32 v[72:73], v[72:73], v[124:125], v[80:81] op_sel:[0,1,0] neg_lo:[0,0,1] neg_hi:[0,0,1]
	v_pk_fma_f32 v[126:127], v[68:69], v[122:123], v[94:95]
	v_pk_fma_f32 v[130:131], v[68:69], v[130:131], v[72:73]
	v_pk_mul_f32 v[68:69], v[82:83], v[92:93] op_sel_hi:[1,0]
	v_pk_mul_f32 v[72:73], v[82:83], v[92:93] op_sel:[0,1]
	v_pk_fma_f32 v[68:69], v[74:75], v[124:125], v[68:69] op_sel_hi:[1,0,1] neg_lo:[0,0,1] neg_hi:[0,0,1]
	v_pk_fma_f32 v[72:73], v[74:75], v[124:125], v[72:73] op_sel:[0,1,0] neg_lo:[0,0,1] neg_hi:[0,0,1]
	v_pk_fma_f32 v[138:139], v[70:71], v[138:139], v[68:69]
	v_pk_mul_f32 v[68:69], v[56:57], v[92:93] op_sel_hi:[1,0]
	v_pk_mul_f32 v[56:57], v[56:57], v[92:93] op_sel:[0,1]
	v_pk_fma_f32 v[140:141], v[70:71], v[140:141], v[72:73]
	v_pk_fma_f32 v[68:69], v[52:53], v[124:125], v[68:69] op_sel_hi:[1,0,1] neg_lo:[0,0,1] neg_hi:[0,0,1]
	v_pk_fma_f32 v[52:53], v[52:53], v[124:125], v[56:57] op_sel:[0,1,0] neg_lo:[0,0,1] neg_hi:[0,0,1]
	v_pk_fma_f32 v[142:143], v[44:45], v[142:143], v[68:69]
	v_pk_fma_f32 v[146:147], v[44:45], v[146:147], v[52:53]
	v_pk_mul_f32 v[44:45], v[58:59], v[92:93] op_sel_hi:[1,0]
	v_pk_mul_f32 v[52:53], v[58:59], v[92:93] op_sel:[0,1]
	s_waitcnt lgkmcnt(0)
	v_pk_mul_f32 v[148:149], v[118:119], v[138:139]
	v_pk_mul_f32 v[118:119], v[118:119], v[140:141]
	v_pk_fma_f32 v[44:45], v[54:55], v[124:125], v[44:45] op_sel_hi:[1,0,1] neg_lo:[0,0,1] neg_hi:[0,0,1]
	v_pk_fma_f32 v[52:53], v[54:55], v[124:125], v[52:53] op_sel:[0,1,0] neg_lo:[0,0,1] neg_hi:[0,0,1]
	v_pk_fma_f32 v[148:149], v[116:117], v[126:127], v[148:149]
	v_pk_fma_f32 v[116:117], v[116:117], v[130:131], v[118:119]
	v_pk_mul_f32 v[118:119], v[110:111], v[138:139]
	v_pk_mul_f32 v[110:111], v[110:111], v[140:141]
	v_pk_fma_f32 v[136:137], v[46:47], v[136:137], v[44:45]
	v_pk_fma_f32 v[144:145], v[46:47], v[144:145], v[52:53]
	v_pk_fma_f32 v[118:119], v[108:109], v[126:127], v[118:119]
	v_pk_fma_f32 v[108:109], v[108:109], v[130:131], v[110:111]
	v_pk_fma_f32 v[110:111], v[88:89], v[142:143], v[148:149]
	v_pk_fma_f32 v[88:89], v[88:89], v[146:147], v[116:117]
	ds_read_b128 v[92:95], v160 offset:7856
	ds_read_b128 v[68:71], v160 offset:8096
	ds_read_b128 v[44:47], v160 offset:8112
	ds_read_b128 v[72:75], v160 offset:8352
	ds_read_b128 v[52:55], v160 offset:8368
	ds_read_b128 v[80:83], v160 offset:8608
	ds_read_b128 v[56:59], v160 offset:8624
	ds_read_b128 v[104:107], v160 offset:8864
	ds_read_b128 v[96:99], v160 offset:8880
	ds_read_b64 v[122:123], v161 offset:9120
	ds_read_b128 v[112:115], v160 offset:7840
	ds_read_b64 v[124:125], v159 offset:9376
	v_pk_fma_f32 v[116:117], v[100:101], v[142:143], v[118:119]
	v_pk_fma_f32 v[100:101], v[100:101], v[146:147], v[108:109]
	v_pk_fma_f32 v[108:109], v[90:91], v[136:137], v[110:111]
	v_pk_fma_f32 v[88:89], v[90:91], v[144:145], v[88:89]
	v_pk_fma_f32 v[90:91], v[102:103], v[136:137], v[116:117]
	v_pk_fma_f32 v[100:101], v[102:103], v[144:145], v[100:101]
	v_add_f32_e32 v89, v88, v89
	v_add_f32_e32 v88, v108, v109
	s_nop 1
	v_add_f32_dpp v88, v88, v88 quad_perm:[1,0,3,2] row_mask:0xf bank_mask:0xf bound_ctrl:1
	v_add_f32_dpp v89, v89, v89 quad_perm:[1,0,3,2] row_mask:0xf bank_mask:0xf bound_ctrl:1
	s_nop 1
	v_add_f32_e32 v90, v90, v91
	v_add_f32_e32 v91, v100, v101
	v_add_f32_dpp v88, v88, v88 quad_perm:[2,3,0,1] row_mask:0xf bank_mask:0xf bound_ctrl:1
	v_add_f32_dpp v89, v89, v89 quad_perm:[2,3,0,1] row_mask:0xf bank_mask:0xf bound_ctrl:1
	v_add_f32_dpp v90, v90, v90 quad_perm:[1,0,3,2] row_mask:0xf bank_mask:0xf bound_ctrl:1
	v_add_f32_dpp v91, v91, v91 quad_perm:[1,0,3,2] row_mask:0xf bank_mask:0xf bound_ctrl:1
	v_add_f32_dpp v88, v88, v88 row_half_mirror row_mask:0xf bank_mask:0xf bound_ctrl:1
	v_add_f32_dpp v89, v89, v89 row_half_mirror row_mask:0xf bank_mask:0xf bound_ctrl:1
	v_add_f32_dpp v90, v90, v90 quad_perm:[2,3,0,1] row_mask:0xf bank_mask:0xf bound_ctrl:1
	v_add_f32_dpp v91, v91, v91 quad_perm:[2,3,0,1] row_mask:0xf bank_mask:0xf bound_ctrl:1
	s_nop 0
	v_mov_b32_dpp v100, v90 row_half_mirror row_mask:0xf bank_mask:0xf bound_ctrl:1
	v_mov_b32_dpp v101, v91 row_half_mirror row_mask:0xf bank_mask:0xf bound_ctrl:1
	s_and_saveexec_b64 s[28:29], s[8:9]
	s_cbranch_execz .LBB0_883
	v_pk_add_f32 v[90:91], v[90:91], v[100:101]
	v_readlane_b32 s30, v253, 40
	v_pk_fma_f32 v[90:91], v[120:121], v[128:129], v[90:91] op_sel:[0,1,0]
	v_readlane_b32 s31, v253, 41
	v_pk_fma_f32 v[90:91], v[128:129], v[88:89], v[90:91] op_sel_hi:[0,1,1] neg_lo:[1,0,0] neg_hi:[1,0,0]
	s_nop 0
	v_lshl_add_u64 v[100:101], v[134:135], 0, s[30:31]
	flat_store_dwordx2 v[100:101], v[90:91]
.LBB0_883:
	s_or_b64 exec, exec, s[28:29]
	v_pk_mul_f32 v[90:91], v[84:85], v[88:89] op_sel_hi:[1,0]
	v_pk_mul_f32 v[84:85], v[84:85], v[88:89] op_sel:[0,1]
	v_pk_fma_f32 v[90:91], v[76:77], v[120:121], v[90:91] op_sel_hi:[1,0,1] neg_lo:[0,0,1] neg_hi:[0,0,1]
	v_pk_fma_f32 v[76:77], v[76:77], v[120:121], v[84:85] op_sel:[0,1,0] neg_lo:[0,0,1] neg_hi:[0,0,1]
	v_pk_fma_f32 v[128:129], v[64:65], v[126:127], v[90:91]
	v_pk_fma_f32 v[130:131], v[64:65], v[130:131], v[76:77]
	v_pk_mul_f32 v[64:65], v[86:87], v[88:89] op_sel_hi:[1,0]
	v_pk_mul_f32 v[76:77], v[86:87], v[88:89] op_sel:[0,1]
	v_pk_fma_f32 v[64:65], v[78:79], v[120:121], v[64:65] op_sel_hi:[1,0,1] neg_lo:[0,0,1] neg_hi:[0,0,1]
	v_pk_fma_f32 v[76:77], v[78:79], v[120:121], v[76:77] op_sel:[0,1,0] neg_lo:[0,0,1] neg_hi:[0,0,1]
	v_pk_fma_f32 v[138:139], v[66:67], v[138:139], v[64:65]
	v_pk_mul_f32 v[64:65], v[60:61], v[88:89] op_sel_hi:[1,0]
	v_pk_mul_f32 v[60:61], v[60:61], v[88:89] op_sel:[0,1]
	v_pk_fma_f32 v[140:141], v[66:67], v[140:141], v[76:77]
	v_pk_fma_f32 v[64:65], v[48:49], v[120:121], v[64:65] op_sel_hi:[1,0,1] neg_lo:[0,0,1] neg_hi:[0,0,1]
	v_pk_fma_f32 v[48:49], v[48:49], v[120:121], v[60:61] op_sel:[0,1,0] neg_lo:[0,0,1] neg_hi:[0,0,1]
	v_pk_fma_f32 v[142:143], v[40:41], v[142:143], v[64:65]
	v_pk_fma_f32 v[146:147], v[40:41], v[146:147], v[48:49]
	v_pk_mul_f32 v[40:41], v[62:63], v[88:89] op_sel_hi:[1,0]
	v_pk_mul_f32 v[48:49], v[62:63], v[88:89] op_sel:[0,1]
	s_waitcnt lgkmcnt(0)
	v_pk_mul_f32 v[148:149], v[114:115], v[138:139]
	v_pk_mul_f32 v[114:115], v[114:115], v[140:141]
	v_pk_fma_f32 v[40:41], v[50:51], v[120:121], v[40:41] op_sel_hi:[1,0,1] neg_lo:[0,0,1] neg_hi:[0,0,1]
	v_pk_fma_f32 v[48:49], v[50:51], v[120:121], v[48:49] op_sel:[0,1,0] neg_lo:[0,0,1] neg_hi:[0,0,1]
	v_pk_fma_f32 v[148:149], v[112:113], v[128:129], v[148:149]
	v_pk_fma_f32 v[112:113], v[112:113], v[130:131], v[114:115]
	v_pk_mul_f32 v[114:115], v[106:107], v[138:139]
	v_pk_mul_f32 v[106:107], v[106:107], v[140:141]
	v_pk_fma_f32 v[136:137], v[42:43], v[136:137], v[40:41]
	v_pk_fma_f32 v[144:145], v[42:43], v[144:145], v[48:49]
	v_pk_fma_f32 v[114:115], v[104:105], v[128:129], v[114:115]
	v_pk_fma_f32 v[104:105], v[104:105], v[130:131], v[106:107]
	v_pk_fma_f32 v[106:107], v[92:93], v[142:143], v[148:149]
	v_pk_fma_f32 v[92:93], v[92:93], v[146:147], v[112:113]
	ds_read_b128 v[88:91], v160 offset:9424
	ds_read_b128 v[64:67], v160 offset:9664
	ds_read_b128 v[40:43], v160 offset:9680
	ds_read_b128 v[76:79], v160 offset:9920
	ds_read_b128 v[48:51], v160 offset:9936
	ds_read_b128 v[84:87], v160 offset:10176
	ds_read_b128 v[60:63], v160 offset:10192
	ds_read_b128 v[108:111], v160 offset:10432
	ds_read_b128 v[100:103], v160 offset:10448
	ds_read_b64 v[120:121], v161 offset:10688
	ds_read_b128 v[116:119], v160 offset:9408
	ds_read_b64 v[126:127], v159 offset:10944
	v_pk_fma_f32 v[112:113], v[96:97], v[142:143], v[114:115]
	v_pk_fma_f32 v[96:97], v[96:97], v[146:147], v[104:105]
	v_pk_fma_f32 v[104:105], v[94:95], v[136:137], v[106:107]
	v_pk_fma_f32 v[92:93], v[94:95], v[144:145], v[92:93]
	v_pk_fma_f32 v[94:95], v[98:99], v[136:137], v[112:113]
	v_pk_fma_f32 v[96:97], v[98:99], v[144:145], v[96:97]
	v_add_f32_e32 v93, v92, v93
	v_add_f32_e32 v92, v104, v105
	s_nop 1
	v_add_f32_dpp v92, v92, v92 quad_perm:[1,0,3,2] row_mask:0xf bank_mask:0xf bound_ctrl:1
	v_add_f32_dpp v93, v93, v93 quad_perm:[1,0,3,2] row_mask:0xf bank_mask:0xf bound_ctrl:1
	s_nop 1
	v_add_f32_e32 v94, v94, v95
	v_add_f32_e32 v95, v96, v97
	v_add_f32_dpp v92, v92, v92 quad_perm:[2,3,0,1] row_mask:0xf bank_mask:0xf bound_ctrl:1
	v_add_f32_dpp v93, v93, v93 quad_perm:[2,3,0,1] row_mask:0xf bank_mask:0xf bound_ctrl:1
	v_add_f32_dpp v94, v94, v94 quad_perm:[1,0,3,2] row_mask:0xf bank_mask:0xf bound_ctrl:1
	v_add_f32_dpp v95, v95, v95 quad_perm:[1,0,3,2] row_mask:0xf bank_mask:0xf bound_ctrl:1
	v_add_f32_dpp v92, v92, v92 row_half_mirror row_mask:0xf bank_mask:0xf bound_ctrl:1
	v_add_f32_dpp v93, v93, v93 row_half_mirror row_mask:0xf bank_mask:0xf bound_ctrl:1
	v_add_f32_dpp v94, v94, v94 quad_perm:[2,3,0,1] row_mask:0xf bank_mask:0xf bound_ctrl:1
	v_add_f32_dpp v95, v95, v95 quad_perm:[2,3,0,1] row_mask:0xf bank_mask:0xf bound_ctrl:1
	s_nop 0
	v_mov_b32_dpp v96, v94 row_half_mirror row_mask:0xf bank_mask:0xf bound_ctrl:1
	v_mov_b32_dpp v97, v95 row_half_mirror row_mask:0xf bank_mask:0xf bound_ctrl:1
	s_and_saveexec_b64 s[28:29], s[8:9]
	s_cbranch_execz .LBB0_885
	v_pk_add_f32 v[94:95], v[94:95], v[96:97]
	v_readlane_b32 s30, v254, 1
	v_pk_fma_f32 v[94:95], v[122:123], v[124:125], v[94:95] op_sel:[0,1,0]
	v_readlane_b32 s31, v254, 2
	v_pk_fma_f32 v[94:95], v[124:125], v[92:93], v[94:95] op_sel_hi:[0,1,1] neg_lo:[1,0,0] neg_hi:[1,0,0]
	s_nop 0
	v_lshl_add_u64 v[96:97], v[134:135], 0, s[30:31]
	flat_store_dwordx2 v[96:97], v[94:95]
.LBB0_885:
	s_or_b64 exec, exec, s[28:29]
	v_pk_mul_f32 v[94:95], v[80:81], v[92:93] op_sel_hi:[1,0]
	v_pk_mul_f32 v[80:81], v[80:81], v[92:93] op_sel:[0,1]
	v_pk_fma_f32 v[94:95], v[72:73], v[122:123], v[94:95] op_sel_hi:[1,0,1] neg_lo:[0,0,1] neg_hi:[0,0,1]
	v_pk_fma_f32 v[72:73], v[72:73], v[122:123], v[80:81] op_sel:[0,1,0] neg_lo:[0,0,1] neg_hi:[0,0,1]
	v_pk_fma_f32 v[128:129], v[68:69], v[128:129], v[94:95]
	v_pk_fma_f32 v[130:131], v[68:69], v[130:131], v[72:73]
	v_pk_mul_f32 v[68:69], v[82:83], v[92:93] op_sel_hi:[1,0]
	v_pk_mul_f32 v[72:73], v[82:83], v[92:93] op_sel:[0,1]
	v_pk_fma_f32 v[68:69], v[74:75], v[122:123], v[68:69] op_sel_hi:[1,0,1] neg_lo:[0,0,1] neg_hi:[0,0,1]
	v_pk_fma_f32 v[72:73], v[74:75], v[122:123], v[72:73] op_sel:[0,1,0] neg_lo:[0,0,1] neg_hi:[0,0,1]
	v_pk_fma_f32 v[138:139], v[70:71], v[138:139], v[68:69]
	v_pk_mul_f32 v[68:69], v[56:57], v[92:93] op_sel_hi:[1,0]
	v_pk_mul_f32 v[56:57], v[56:57], v[92:93] op_sel:[0,1]
	v_pk_fma_f32 v[140:141], v[70:71], v[140:141], v[72:73]
	v_pk_fma_f32 v[68:69], v[52:53], v[122:123], v[68:69] op_sel_hi:[1,0,1] neg_lo:[0,0,1] neg_hi:[0,0,1]
	v_pk_fma_f32 v[52:53], v[52:53], v[122:123], v[56:57] op_sel:[0,1,0] neg_lo:[0,0,1] neg_hi:[0,0,1]
	v_pk_fma_f32 v[142:143], v[44:45], v[142:143], v[68:69]
	v_pk_fma_f32 v[146:147], v[44:45], v[146:147], v[52:53]
	v_pk_mul_f32 v[44:45], v[58:59], v[92:93] op_sel_hi:[1,0]
	v_pk_mul_f32 v[52:53], v[58:59], v[92:93] op_sel:[0,1]
	s_waitcnt lgkmcnt(0)
	v_pk_mul_f32 v[148:149], v[118:119], v[138:139]
	v_pk_mul_f32 v[118:119], v[118:119], v[140:141]
	v_pk_fma_f32 v[44:45], v[54:55], v[122:123], v[44:45] op_sel_hi:[1,0,1] neg_lo:[0,0,1] neg_hi:[0,0,1]
	v_pk_fma_f32 v[52:53], v[54:55], v[122:123], v[52:53] op_sel:[0,1,0] neg_lo:[0,0,1] neg_hi:[0,0,1]
	v_pk_fma_f32 v[148:149], v[116:117], v[128:129], v[148:149]
	v_pk_fma_f32 v[116:117], v[116:117], v[130:131], v[118:119]
	v_pk_mul_f32 v[118:119], v[110:111], v[138:139]
	v_pk_mul_f32 v[110:111], v[110:111], v[140:141]
	v_pk_fma_f32 v[136:137], v[46:47], v[136:137], v[44:45]
	v_pk_fma_f32 v[144:145], v[46:47], v[144:145], v[52:53]
	v_pk_fma_f32 v[118:119], v[108:109], v[128:129], v[118:119]
	v_pk_fma_f32 v[108:109], v[108:109], v[130:131], v[110:111]
	v_pk_fma_f32 v[110:111], v[88:89], v[142:143], v[148:149]
	v_pk_fma_f32 v[88:89], v[88:89], v[146:147], v[116:117]
	ds_read_b128 v[92:95], v160 offset:10992
	ds_read_b128 v[68:71], v160 offset:11232
	ds_read_b128 v[44:47], v160 offset:11248
	ds_read_b128 v[72:75], v160 offset:11488
	ds_read_b128 v[52:55], v160 offset:11504
	ds_read_b128 v[80:83], v160 offset:11744
	ds_read_b128 v[56:59], v160 offset:11760
	ds_read_b128 v[104:107], v160 offset:12000
	ds_read_b128 v[96:99], v160 offset:12016
	ds_read_b64 v[122:123], v161 offset:12256
	ds_read_b128 v[112:115], v160 offset:10976
	ds_read_b64 v[124:125], v159 offset:12512
	v_pk_fma_f32 v[116:117], v[100:101], v[142:143], v[118:119]
	v_pk_fma_f32 v[100:101], v[100:101], v[146:147], v[108:109]
	v_pk_fma_f32 v[108:109], v[90:91], v[136:137], v[110:111]
	v_pk_fma_f32 v[88:89], v[90:91], v[144:145], v[88:89]
	v_pk_fma_f32 v[90:91], v[102:103], v[136:137], v[116:117]
	v_pk_fma_f32 v[100:101], v[102:103], v[144:145], v[100:101]
	v_add_f32_e32 v89, v88, v89
	v_add_f32_e32 v88, v108, v109
	s_nop 1
	v_add_f32_dpp v88, v88, v88 quad_perm:[1,0,3,2] row_mask:0xf bank_mask:0xf bound_ctrl:1
	v_add_f32_dpp v89, v89, v89 quad_perm:[1,0,3,2] row_mask:0xf bank_mask:0xf bound_ctrl:1
	s_nop 1
	v_add_f32_e32 v90, v90, v91
	v_add_f32_e32 v91, v100, v101
	v_add_f32_dpp v88, v88, v88 quad_perm:[2,3,0,1] row_mask:0xf bank_mask:0xf bound_ctrl:1
	v_add_f32_dpp v89, v89, v89 quad_perm:[2,3,0,1] row_mask:0xf bank_mask:0xf bound_ctrl:1
	v_add_f32_dpp v90, v90, v90 quad_perm:[1,0,3,2] row_mask:0xf bank_mask:0xf bound_ctrl:1
	v_add_f32_dpp v91, v91, v91 quad_perm:[1,0,3,2] row_mask:0xf bank_mask:0xf bound_ctrl:1
	v_add_f32_dpp v88, v88, v88 row_half_mirror row_mask:0xf bank_mask:0xf bound_ctrl:1
	v_add_f32_dpp v89, v89, v89 row_half_mirror row_mask:0xf bank_mask:0xf bound_ctrl:1
	v_add_f32_dpp v90, v90, v90 quad_perm:[2,3,0,1] row_mask:0xf bank_mask:0xf bound_ctrl:1
	v_add_f32_dpp v91, v91, v91 quad_perm:[2,3,0,1] row_mask:0xf bank_mask:0xf bound_ctrl:1
	s_nop 0
	v_mov_b32_dpp v100, v90 row_half_mirror row_mask:0xf bank_mask:0xf bound_ctrl:1
	v_mov_b32_dpp v101, v91 row_half_mirror row_mask:0xf bank_mask:0xf bound_ctrl:1
	s_and_saveexec_b64 s[28:29], s[8:9]
	s_cbranch_execz .LBB0_887
	v_pk_add_f32 v[90:91], v[90:91], v[100:101]
	v_readlane_b32 s30, v254, 3
	v_pk_fma_f32 v[90:91], v[120:121], v[126:127], v[90:91] op_sel:[0,1,0]
	v_readlane_b32 s31, v254, 4
	v_pk_fma_f32 v[90:91], v[126:127], v[88:89], v[90:91] op_sel_hi:[0,1,1] neg_lo:[1,0,0] neg_hi:[1,0,0]
	s_nop 0
	v_lshl_add_u64 v[100:101], v[134:135], 0, s[30:31]
	flat_store_dwordx2 v[100:101], v[90:91]
.LBB0_887:
	s_or_b64 exec, exec, s[28:29]
	v_pk_mul_f32 v[90:91], v[84:85], v[88:89] op_sel_hi:[1,0]
	v_pk_mul_f32 v[84:85], v[84:85], v[88:89] op_sel:[0,1]
	v_pk_fma_f32 v[90:91], v[76:77], v[120:121], v[90:91] op_sel_hi:[1,0,1] neg_lo:[0,0,1] neg_hi:[0,0,1]
	v_pk_fma_f32 v[76:77], v[76:77], v[120:121], v[84:85] op_sel:[0,1,0] neg_lo:[0,0,1] neg_hi:[0,0,1]
	v_pk_fma_f32 v[128:129], v[64:65], v[128:129], v[90:91]
	v_pk_fma_f32 v[130:131], v[64:65], v[130:131], v[76:77]
	v_pk_mul_f32 v[64:65], v[86:87], v[88:89] op_sel_hi:[1,0]
	v_pk_mul_f32 v[76:77], v[86:87], v[88:89] op_sel:[0,1]
	v_pk_fma_f32 v[64:65], v[78:79], v[120:121], v[64:65] op_sel_hi:[1,0,1] neg_lo:[0,0,1] neg_hi:[0,0,1]
	v_pk_fma_f32 v[76:77], v[78:79], v[120:121], v[76:77] op_sel:[0,1,0] neg_lo:[0,0,1] neg_hi:[0,0,1]
	v_pk_fma_f32 v[138:139], v[66:67], v[138:139], v[64:65]
	v_pk_mul_f32 v[64:65], v[60:61], v[88:89] op_sel_hi:[1,0]
	v_pk_mul_f32 v[60:61], v[60:61], v[88:89] op_sel:[0,1]
	v_pk_fma_f32 v[140:141], v[66:67], v[140:141], v[76:77]
	v_pk_fma_f32 v[64:65], v[48:49], v[120:121], v[64:65] op_sel_hi:[1,0,1] neg_lo:[0,0,1] neg_hi:[0,0,1]
	v_pk_fma_f32 v[48:49], v[48:49], v[120:121], v[60:61] op_sel:[0,1,0] neg_lo:[0,0,1] neg_hi:[0,0,1]
	v_pk_fma_f32 v[142:143], v[40:41], v[142:143], v[64:65]
	v_pk_fma_f32 v[146:147], v[40:41], v[146:147], v[48:49]
	v_pk_mul_f32 v[40:41], v[62:63], v[88:89] op_sel_hi:[1,0]
	v_pk_mul_f32 v[48:49], v[62:63], v[88:89] op_sel:[0,1]
	s_waitcnt lgkmcnt(0)
	v_pk_mul_f32 v[148:149], v[114:115], v[138:139]
	v_pk_mul_f32 v[114:115], v[114:115], v[140:141]
	v_pk_fma_f32 v[40:41], v[50:51], v[120:121], v[40:41] op_sel_hi:[1,0,1] neg_lo:[0,0,1] neg_hi:[0,0,1]
	v_pk_fma_f32 v[48:49], v[50:51], v[120:121], v[48:49] op_sel:[0,1,0] neg_lo:[0,0,1] neg_hi:[0,0,1]
	v_pk_fma_f32 v[148:149], v[112:113], v[128:129], v[148:149]
	v_pk_fma_f32 v[112:113], v[112:113], v[130:131], v[114:115]
	v_pk_mul_f32 v[114:115], v[106:107], v[138:139]
	v_pk_mul_f32 v[106:107], v[106:107], v[140:141]
	v_pk_fma_f32 v[136:137], v[42:43], v[136:137], v[40:41]
	v_pk_fma_f32 v[144:145], v[42:43], v[144:145], v[48:49]
	v_pk_fma_f32 v[114:115], v[104:105], v[128:129], v[114:115]
	v_pk_fma_f32 v[104:105], v[104:105], v[130:131], v[106:107]
	v_pk_fma_f32 v[106:107], v[92:93], v[142:143], v[148:149]
	v_pk_fma_f32 v[92:93], v[92:93], v[146:147], v[112:113]
	ds_read_b128 v[88:91], v160 offset:12560
	ds_read_b128 v[64:67], v160 offset:12800
	ds_read_b128 v[40:43], v160 offset:12816
	ds_read_b128 v[76:79], v160 offset:13056
	ds_read_b128 v[48:51], v160 offset:13072
	ds_read_b128 v[84:87], v160 offset:13312
	ds_read_b128 v[60:63], v160 offset:13328
	ds_read_b128 v[108:111], v160 offset:13568
	ds_read_b128 v[100:103], v160 offset:13584
	ds_read_b64 v[120:121], v161 offset:13824
	ds_read_b128 v[116:119], v160 offset:12544
	ds_read_b64 v[126:127], v159 offset:14080
	v_pk_fma_f32 v[112:113], v[96:97], v[142:143], v[114:115]
	v_pk_fma_f32 v[96:97], v[96:97], v[146:147], v[104:105]
	v_pk_fma_f32 v[104:105], v[94:95], v[136:137], v[106:107]
	v_pk_fma_f32 v[92:93], v[94:95], v[144:145], v[92:93]
	v_pk_fma_f32 v[94:95], v[98:99], v[136:137], v[112:113]
	v_pk_fma_f32 v[96:97], v[98:99], v[144:145], v[96:97]
	v_add_f32_e32 v93, v92, v93
	v_add_f32_e32 v92, v104, v105
	s_nop 1
	v_add_f32_dpp v92, v92, v92 quad_perm:[1,0,3,2] row_mask:0xf bank_mask:0xf bound_ctrl:1
	v_add_f32_dpp v93, v93, v93 quad_perm:[1,0,3,2] row_mask:0xf bank_mask:0xf bound_ctrl:1
	s_nop 1
	v_add_f32_e32 v94, v94, v95
	v_add_f32_e32 v95, v96, v97
	v_add_f32_dpp v92, v92, v92 quad_perm:[2,3,0,1] row_mask:0xf bank_mask:0xf bound_ctrl:1
	v_add_f32_dpp v93, v93, v93 quad_perm:[2,3,0,1] row_mask:0xf bank_mask:0xf bound_ctrl:1
	v_add_f32_dpp v94, v94, v94 quad_perm:[1,0,3,2] row_mask:0xf bank_mask:0xf bound_ctrl:1
	v_add_f32_dpp v95, v95, v95 quad_perm:[1,0,3,2] row_mask:0xf bank_mask:0xf bound_ctrl:1
	v_add_f32_dpp v92, v92, v92 row_half_mirror row_mask:0xf bank_mask:0xf bound_ctrl:1
	v_add_f32_dpp v93, v93, v93 row_half_mirror row_mask:0xf bank_mask:0xf bound_ctrl:1
	v_add_f32_dpp v94, v94, v94 quad_perm:[2,3,0,1] row_mask:0xf bank_mask:0xf bound_ctrl:1
	v_add_f32_dpp v95, v95, v95 quad_perm:[2,3,0,1] row_mask:0xf bank_mask:0xf bound_ctrl:1
	s_nop 0
	v_mov_b32_dpp v96, v94 row_half_mirror row_mask:0xf bank_mask:0xf bound_ctrl:1
	v_mov_b32_dpp v97, v95 row_half_mirror row_mask:0xf bank_mask:0xf bound_ctrl:1
	s_and_saveexec_b64 s[28:29], s[8:9]
	s_cbranch_execz .LBB0_889
	v_pk_add_f32 v[94:95], v[94:95], v[96:97]
	v_readlane_b32 s30, v254, 5
	v_pk_fma_f32 v[94:95], v[122:123], v[124:125], v[94:95] op_sel:[0,1,0]
	v_readlane_b32 s31, v254, 6
	v_pk_fma_f32 v[94:95], v[124:125], v[92:93], v[94:95] op_sel_hi:[0,1,1] neg_lo:[1,0,0] neg_hi:[1,0,0]
	s_nop 0
	v_lshl_add_u64 v[96:97], v[134:135], 0, s[30:31]
	flat_store_dwordx2 v[96:97], v[94:95]
.LBB0_889:
	s_or_b64 exec, exec, s[28:29]
	v_pk_mul_f32 v[94:95], v[80:81], v[92:93] op_sel_hi:[1,0]
	v_pk_mul_f32 v[80:81], v[80:81], v[92:93] op_sel:[0,1]
	v_pk_fma_f32 v[94:95], v[72:73], v[122:123], v[94:95] op_sel_hi:[1,0,1] neg_lo:[0,0,1] neg_hi:[0,0,1]
	v_pk_fma_f32 v[72:73], v[72:73], v[122:123], v[80:81] op_sel:[0,1,0] neg_lo:[0,0,1] neg_hi:[0,0,1]
	v_pk_fma_f32 v[128:129], v[68:69], v[128:129], v[94:95]
	v_pk_fma_f32 v[130:131], v[68:69], v[130:131], v[72:73]
	v_pk_mul_f32 v[68:69], v[82:83], v[92:93] op_sel_hi:[1,0]
	v_pk_mul_f32 v[72:73], v[82:83], v[92:93] op_sel:[0,1]
	v_pk_fma_f32 v[68:69], v[74:75], v[122:123], v[68:69] op_sel_hi:[1,0,1] neg_lo:[0,0,1] neg_hi:[0,0,1]
	v_pk_fma_f32 v[72:73], v[74:75], v[122:123], v[72:73] op_sel:[0,1,0] neg_lo:[0,0,1] neg_hi:[0,0,1]
	v_pk_fma_f32 v[138:139], v[70:71], v[138:139], v[68:69]
	v_pk_mul_f32 v[68:69], v[56:57], v[92:93] op_sel_hi:[1,0]
	v_pk_mul_f32 v[56:57], v[56:57], v[92:93] op_sel:[0,1]
	v_pk_fma_f32 v[140:141], v[70:71], v[140:141], v[72:73]
	v_pk_fma_f32 v[68:69], v[52:53], v[122:123], v[68:69] op_sel_hi:[1,0,1] neg_lo:[0,0,1] neg_hi:[0,0,1]
	v_pk_fma_f32 v[52:53], v[52:53], v[122:123], v[56:57] op_sel:[0,1,0] neg_lo:[0,0,1] neg_hi:[0,0,1]
	v_pk_fma_f32 v[142:143], v[44:45], v[142:143], v[68:69]
	v_pk_fma_f32 v[146:147], v[44:45], v[146:147], v[52:53]
	v_pk_mul_f32 v[44:45], v[58:59], v[92:93] op_sel_hi:[1,0]
	v_pk_mul_f32 v[52:53], v[58:59], v[92:93] op_sel:[0,1]
	s_waitcnt lgkmcnt(0)
	v_pk_mul_f32 v[148:149], v[118:119], v[138:139]
	v_pk_mul_f32 v[118:119], v[118:119], v[140:141]
	v_pk_fma_f32 v[44:45], v[54:55], v[122:123], v[44:45] op_sel_hi:[1,0,1] neg_lo:[0,0,1] neg_hi:[0,0,1]
	v_pk_fma_f32 v[52:53], v[54:55], v[122:123], v[52:53] op_sel:[0,1,0] neg_lo:[0,0,1] neg_hi:[0,0,1]
	v_pk_fma_f32 v[148:149], v[116:117], v[128:129], v[148:149]
	v_pk_fma_f32 v[116:117], v[116:117], v[130:131], v[118:119]
	v_pk_mul_f32 v[118:119], v[110:111], v[138:139]
	v_pk_mul_f32 v[110:111], v[110:111], v[140:141]
	v_pk_fma_f32 v[136:137], v[46:47], v[136:137], v[44:45]
	v_pk_fma_f32 v[144:145], v[46:47], v[144:145], v[52:53]
	v_pk_fma_f32 v[118:119], v[108:109], v[128:129], v[118:119]
	v_pk_fma_f32 v[108:109], v[108:109], v[130:131], v[110:111]
	v_pk_fma_f32 v[110:111], v[88:89], v[142:143], v[148:149]
	v_pk_fma_f32 v[88:89], v[88:89], v[146:147], v[116:117]
	ds_read_b128 v[92:95], v160 offset:14128
	ds_read_b128 v[68:71], v160 offset:14368
	ds_read_b128 v[44:47], v160 offset:14384
	ds_read_b128 v[72:75], v160 offset:14624
	ds_read_b128 v[52:55], v160 offset:14640
	ds_read_b128 v[80:83], v160 offset:14880
	ds_read_b128 v[56:59], v160 offset:14896
	ds_read_b128 v[104:107], v160 offset:15136
	ds_read_b128 v[96:99], v160 offset:15152
	ds_read_b64 v[122:123], v161 offset:15392
	ds_read_b128 v[112:115], v160 offset:14112
	ds_read_b64 v[124:125], v159 offset:15648
	v_pk_fma_f32 v[116:117], v[100:101], v[142:143], v[118:119]
	v_pk_fma_f32 v[100:101], v[100:101], v[146:147], v[108:109]
	v_pk_fma_f32 v[108:109], v[90:91], v[136:137], v[110:111]
	v_pk_fma_f32 v[88:89], v[90:91], v[144:145], v[88:89]
	v_pk_fma_f32 v[90:91], v[102:103], v[136:137], v[116:117]
	v_pk_fma_f32 v[100:101], v[102:103], v[144:145], v[100:101]
	v_add_f32_e32 v89, v88, v89
	v_add_f32_e32 v88, v108, v109
	s_nop 1
	v_add_f32_dpp v88, v88, v88 quad_perm:[1,0,3,2] row_mask:0xf bank_mask:0xf bound_ctrl:1
	v_add_f32_dpp v89, v89, v89 quad_perm:[1,0,3,2] row_mask:0xf bank_mask:0xf bound_ctrl:1
	s_nop 1
	v_add_f32_e32 v90, v90, v91
	v_add_f32_e32 v91, v100, v101
	v_add_f32_dpp v88, v88, v88 quad_perm:[2,3,0,1] row_mask:0xf bank_mask:0xf bound_ctrl:1
	v_add_f32_dpp v89, v89, v89 quad_perm:[2,3,0,1] row_mask:0xf bank_mask:0xf bound_ctrl:1
	v_add_f32_dpp v90, v90, v90 quad_perm:[1,0,3,2] row_mask:0xf bank_mask:0xf bound_ctrl:1
	v_add_f32_dpp v91, v91, v91 quad_perm:[1,0,3,2] row_mask:0xf bank_mask:0xf bound_ctrl:1
	v_add_f32_dpp v88, v88, v88 row_half_mirror row_mask:0xf bank_mask:0xf bound_ctrl:1
	v_add_f32_dpp v89, v89, v89 row_half_mirror row_mask:0xf bank_mask:0xf bound_ctrl:1
	v_add_f32_dpp v90, v90, v90 quad_perm:[2,3,0,1] row_mask:0xf bank_mask:0xf bound_ctrl:1
	v_add_f32_dpp v91, v91, v91 quad_perm:[2,3,0,1] row_mask:0xf bank_mask:0xf bound_ctrl:1
	s_nop 0
	v_mov_b32_dpp v100, v90 row_half_mirror row_mask:0xf bank_mask:0xf bound_ctrl:1
	v_mov_b32_dpp v101, v91 row_half_mirror row_mask:0xf bank_mask:0xf bound_ctrl:1
	s_and_saveexec_b64 s[28:29], s[8:9]
	s_cbranch_execz .LBB0_891
	v_pk_add_f32 v[90:91], v[90:91], v[100:101]
	v_readlane_b32 s30, v253, 42
	v_pk_fma_f32 v[90:91], v[120:121], v[126:127], v[90:91] op_sel:[0,1,0]
	v_readlane_b32 s31, v253, 43
	v_pk_fma_f32 v[90:91], v[126:127], v[88:89], v[90:91] op_sel_hi:[0,1,1] neg_lo:[1,0,0] neg_hi:[1,0,0]
	s_nop 0
	v_lshl_add_u64 v[100:101], v[134:135], 0, s[30:31]
	flat_store_dwordx2 v[100:101], v[90:91]
.LBB0_891:
	s_or_b64 exec, exec, s[28:29]
	v_pk_mul_f32 v[90:91], v[84:85], v[88:89] op_sel_hi:[1,0]
	v_pk_mul_f32 v[84:85], v[84:85], v[88:89] op_sel:[0,1]
	v_pk_fma_f32 v[90:91], v[76:77], v[120:121], v[90:91] op_sel_hi:[1,0,1] neg_lo:[0,0,1] neg_hi:[0,0,1]
	v_pk_fma_f32 v[76:77], v[76:77], v[120:121], v[84:85] op_sel:[0,1,0] neg_lo:[0,0,1] neg_hi:[0,0,1]
	v_pk_fma_f32 v[128:129], v[64:65], v[128:129], v[90:91]
	v_pk_fma_f32 v[130:131], v[64:65], v[130:131], v[76:77]
	v_pk_mul_f32 v[64:65], v[86:87], v[88:89] op_sel_hi:[1,0]
	v_pk_mul_f32 v[76:77], v[86:87], v[88:89] op_sel:[0,1]
	v_pk_fma_f32 v[64:65], v[78:79], v[120:121], v[64:65] op_sel_hi:[1,0,1] neg_lo:[0,0,1] neg_hi:[0,0,1]
	v_pk_fma_f32 v[76:77], v[78:79], v[120:121], v[76:77] op_sel:[0,1,0] neg_lo:[0,0,1] neg_hi:[0,0,1]
	v_pk_fma_f32 v[138:139], v[66:67], v[138:139], v[64:65]
	v_pk_mul_f32 v[64:65], v[60:61], v[88:89] op_sel_hi:[1,0]
	v_pk_mul_f32 v[60:61], v[60:61], v[88:89] op_sel:[0,1]
	v_pk_fma_f32 v[140:141], v[66:67], v[140:141], v[76:77]
	v_pk_fma_f32 v[64:65], v[48:49], v[120:121], v[64:65] op_sel_hi:[1,0,1] neg_lo:[0,0,1] neg_hi:[0,0,1]
	v_pk_fma_f32 v[48:49], v[48:49], v[120:121], v[60:61] op_sel:[0,1,0] neg_lo:[0,0,1] neg_hi:[0,0,1]
	v_pk_fma_f32 v[142:143], v[40:41], v[142:143], v[64:65]
	v_pk_fma_f32 v[146:147], v[40:41], v[146:147], v[48:49]
	v_pk_mul_f32 v[40:41], v[62:63], v[88:89] op_sel_hi:[1,0]
	v_pk_mul_f32 v[48:49], v[62:63], v[88:89] op_sel:[0,1]
	s_waitcnt lgkmcnt(0)
	v_pk_mul_f32 v[148:149], v[114:115], v[138:139]
	v_pk_mul_f32 v[114:115], v[114:115], v[140:141]
	v_pk_fma_f32 v[40:41], v[50:51], v[120:121], v[40:41] op_sel_hi:[1,0,1] neg_lo:[0,0,1] neg_hi:[0,0,1]
	v_pk_fma_f32 v[48:49], v[50:51], v[120:121], v[48:49] op_sel:[0,1,0] neg_lo:[0,0,1] neg_hi:[0,0,1]
	v_pk_fma_f32 v[148:149], v[112:113], v[128:129], v[148:149]
	v_pk_fma_f32 v[112:113], v[112:113], v[130:131], v[114:115]
	v_pk_mul_f32 v[114:115], v[106:107], v[138:139]
	v_pk_mul_f32 v[106:107], v[106:107], v[140:141]
	v_pk_fma_f32 v[136:137], v[42:43], v[136:137], v[40:41]
	v_pk_fma_f32 v[144:145], v[42:43], v[144:145], v[48:49]
	v_pk_fma_f32 v[114:115], v[104:105], v[128:129], v[114:115]
	v_pk_fma_f32 v[104:105], v[104:105], v[130:131], v[106:107]
	v_pk_fma_f32 v[106:107], v[92:93], v[142:143], v[148:149]
	v_pk_fma_f32 v[92:93], v[92:93], v[146:147], v[112:113]
	ds_read_b128 v[88:91], v160 offset:15696
	ds_read_b128 v[64:67], v160 offset:15936
	ds_read_b128 v[40:43], v160 offset:15952
	ds_read_b128 v[76:79], v160 offset:16192
	ds_read_b128 v[48:51], v160 offset:16208
	ds_read_b128 v[84:87], v160 offset:16448
	ds_read_b128 v[60:63], v160 offset:16464
	ds_read_b128 v[108:111], v160 offset:16704
	ds_read_b128 v[100:103], v160 offset:16720
	ds_read_b64 v[120:121], v161 offset:16960
	ds_read_b128 v[116:119], v160 offset:15680
	ds_read_b64 v[126:127], v159 offset:17216
	v_pk_fma_f32 v[112:113], v[96:97], v[142:143], v[114:115]
	v_pk_fma_f32 v[96:97], v[96:97], v[146:147], v[104:105]
	v_pk_fma_f32 v[104:105], v[94:95], v[136:137], v[106:107]
	v_pk_fma_f32 v[92:93], v[94:95], v[144:145], v[92:93]
	v_pk_fma_f32 v[94:95], v[98:99], v[136:137], v[112:113]
	v_pk_fma_f32 v[96:97], v[98:99], v[144:145], v[96:97]
	v_add_f32_e32 v93, v92, v93
	v_add_f32_e32 v92, v104, v105
	s_nop 1
	v_add_f32_dpp v92, v92, v92 quad_perm:[1,0,3,2] row_mask:0xf bank_mask:0xf bound_ctrl:1
	v_add_f32_dpp v93, v93, v93 quad_perm:[1,0,3,2] row_mask:0xf bank_mask:0xf bound_ctrl:1
	s_nop 1
	v_add_f32_e32 v94, v94, v95
	v_add_f32_e32 v95, v96, v97
	v_add_f32_dpp v92, v92, v92 quad_perm:[2,3,0,1] row_mask:0xf bank_mask:0xf bound_ctrl:1
	v_add_f32_dpp v93, v93, v93 quad_perm:[2,3,0,1] row_mask:0xf bank_mask:0xf bound_ctrl:1
	v_add_f32_dpp v94, v94, v94 quad_perm:[1,0,3,2] row_mask:0xf bank_mask:0xf bound_ctrl:1
	v_add_f32_dpp v95, v95, v95 quad_perm:[1,0,3,2] row_mask:0xf bank_mask:0xf bound_ctrl:1
	v_add_f32_dpp v92, v92, v92 row_half_mirror row_mask:0xf bank_mask:0xf bound_ctrl:1
	v_add_f32_dpp v93, v93, v93 row_half_mirror row_mask:0xf bank_mask:0xf bound_ctrl:1
	v_add_f32_dpp v94, v94, v94 quad_perm:[2,3,0,1] row_mask:0xf bank_mask:0xf bound_ctrl:1
	v_add_f32_dpp v95, v95, v95 quad_perm:[2,3,0,1] row_mask:0xf bank_mask:0xf bound_ctrl:1
	s_nop 0
	v_mov_b32_dpp v96, v94 row_half_mirror row_mask:0xf bank_mask:0xf bound_ctrl:1
	v_mov_b32_dpp v97, v95 row_half_mirror row_mask:0xf bank_mask:0xf bound_ctrl:1
	s_and_saveexec_b64 s[28:29], s[8:9]
	s_cbranch_execz .LBB0_893
	v_pk_add_f32 v[94:95], v[94:95], v[96:97]
	v_readlane_b32 s30, v254, 7
	v_pk_fma_f32 v[94:95], v[122:123], v[124:125], v[94:95] op_sel:[0,1,0]
	v_readlane_b32 s31, v254, 8
	v_pk_fma_f32 v[94:95], v[124:125], v[92:93], v[94:95] op_sel_hi:[0,1,1] neg_lo:[1,0,0] neg_hi:[1,0,0]
	s_nop 0
	v_lshl_add_u64 v[96:97], v[134:135], 0, s[30:31]
	flat_store_dwordx2 v[96:97], v[94:95]
.LBB0_893:
	s_or_b64 exec, exec, s[28:29]
	v_pk_mul_f32 v[94:95], v[80:81], v[92:93] op_sel_hi:[1,0]
	v_pk_mul_f32 v[80:81], v[80:81], v[92:93] op_sel:[0,1]
	v_pk_fma_f32 v[94:95], v[72:73], v[122:123], v[94:95] op_sel_hi:[1,0,1] neg_lo:[0,0,1] neg_hi:[0,0,1]
	v_pk_fma_f32 v[72:73], v[72:73], v[122:123], v[80:81] op_sel:[0,1,0] neg_lo:[0,0,1] neg_hi:[0,0,1]
	v_pk_fma_f32 v[128:129], v[68:69], v[128:129], v[94:95]
	v_pk_fma_f32 v[130:131], v[68:69], v[130:131], v[72:73]
	v_pk_mul_f32 v[68:69], v[82:83], v[92:93] op_sel_hi:[1,0]
	v_pk_mul_f32 v[72:73], v[82:83], v[92:93] op_sel:[0,1]
	v_pk_fma_f32 v[68:69], v[74:75], v[122:123], v[68:69] op_sel_hi:[1,0,1] neg_lo:[0,0,1] neg_hi:[0,0,1]
	v_pk_fma_f32 v[72:73], v[74:75], v[122:123], v[72:73] op_sel:[0,1,0] neg_lo:[0,0,1] neg_hi:[0,0,1]
	v_pk_fma_f32 v[138:139], v[70:71], v[138:139], v[68:69]
	v_pk_mul_f32 v[68:69], v[56:57], v[92:93] op_sel_hi:[1,0]
	v_pk_mul_f32 v[56:57], v[56:57], v[92:93] op_sel:[0,1]
	v_pk_fma_f32 v[140:141], v[70:71], v[140:141], v[72:73]
	v_pk_fma_f32 v[68:69], v[52:53], v[122:123], v[68:69] op_sel_hi:[1,0,1] neg_lo:[0,0,1] neg_hi:[0,0,1]
	v_pk_fma_f32 v[52:53], v[52:53], v[122:123], v[56:57] op_sel:[0,1,0] neg_lo:[0,0,1] neg_hi:[0,0,1]
	v_pk_fma_f32 v[142:143], v[44:45], v[142:143], v[68:69]
	v_pk_fma_f32 v[146:147], v[44:45], v[146:147], v[52:53]
	v_pk_mul_f32 v[44:45], v[58:59], v[92:93] op_sel_hi:[1,0]
	v_pk_mul_f32 v[52:53], v[58:59], v[92:93] op_sel:[0,1]
	s_waitcnt lgkmcnt(0)
	v_pk_mul_f32 v[148:149], v[118:119], v[138:139]
	v_pk_mul_f32 v[118:119], v[118:119], v[140:141]
	v_pk_fma_f32 v[44:45], v[54:55], v[122:123], v[44:45] op_sel_hi:[1,0,1] neg_lo:[0,0,1] neg_hi:[0,0,1]
	v_pk_fma_f32 v[52:53], v[54:55], v[122:123], v[52:53] op_sel:[0,1,0] neg_lo:[0,0,1] neg_hi:[0,0,1]
	v_pk_fma_f32 v[148:149], v[116:117], v[128:129], v[148:149]
	v_pk_fma_f32 v[116:117], v[116:117], v[130:131], v[118:119]
	v_pk_mul_f32 v[118:119], v[110:111], v[138:139]
	v_pk_mul_f32 v[110:111], v[110:111], v[140:141]
	v_pk_fma_f32 v[136:137], v[46:47], v[136:137], v[44:45]
	v_pk_fma_f32 v[144:145], v[46:47], v[144:145], v[52:53]
	v_pk_fma_f32 v[118:119], v[108:109], v[128:129], v[118:119]
	v_pk_fma_f32 v[108:109], v[108:109], v[130:131], v[110:111]
	v_pk_fma_f32 v[110:111], v[88:89], v[142:143], v[148:149]
	v_pk_fma_f32 v[88:89], v[88:89], v[146:147], v[116:117]
	ds_read_b128 v[92:95], v160 offset:17264
	ds_read_b128 v[68:71], v160 offset:17504
	ds_read_b128 v[44:47], v160 offset:17520
	ds_read_b128 v[72:75], v160 offset:17760
	ds_read_b128 v[52:55], v160 offset:17776
	ds_read_b128 v[80:83], v160 offset:18016
	ds_read_b128 v[56:59], v160 offset:18032
	ds_read_b128 v[104:107], v160 offset:18272
	ds_read_b128 v[96:99], v160 offset:18288
	ds_read_b64 v[122:123], v161 offset:18528
	ds_read_b128 v[112:115], v160 offset:17248
	ds_read_b64 v[124:125], v159 offset:18784
	v_pk_fma_f32 v[116:117], v[100:101], v[142:143], v[118:119]
	v_pk_fma_f32 v[100:101], v[100:101], v[146:147], v[108:109]
	v_pk_fma_f32 v[108:109], v[90:91], v[136:137], v[110:111]
	v_pk_fma_f32 v[88:89], v[90:91], v[144:145], v[88:89]
	v_pk_fma_f32 v[90:91], v[102:103], v[136:137], v[116:117]
	v_pk_fma_f32 v[100:101], v[102:103], v[144:145], v[100:101]
	v_add_f32_e32 v89, v88, v89
	v_add_f32_e32 v88, v108, v109
	s_nop 1
	v_add_f32_dpp v88, v88, v88 quad_perm:[1,0,3,2] row_mask:0xf bank_mask:0xf bound_ctrl:1
	v_add_f32_dpp v89, v89, v89 quad_perm:[1,0,3,2] row_mask:0xf bank_mask:0xf bound_ctrl:1
	s_nop 1
	v_add_f32_e32 v90, v90, v91
	v_add_f32_e32 v91, v100, v101
	v_add_f32_dpp v88, v88, v88 quad_perm:[2,3,0,1] row_mask:0xf bank_mask:0xf bound_ctrl:1
	v_add_f32_dpp v89, v89, v89 quad_perm:[2,3,0,1] row_mask:0xf bank_mask:0xf bound_ctrl:1
	v_add_f32_dpp v90, v90, v90 quad_perm:[1,0,3,2] row_mask:0xf bank_mask:0xf bound_ctrl:1
	v_add_f32_dpp v91, v91, v91 quad_perm:[1,0,3,2] row_mask:0xf bank_mask:0xf bound_ctrl:1
	v_add_f32_dpp v88, v88, v88 row_half_mirror row_mask:0xf bank_mask:0xf bound_ctrl:1
	v_add_f32_dpp v89, v89, v89 row_half_mirror row_mask:0xf bank_mask:0xf bound_ctrl:1
	v_add_f32_dpp v90, v90, v90 quad_perm:[2,3,0,1] row_mask:0xf bank_mask:0xf bound_ctrl:1
	v_add_f32_dpp v91, v91, v91 quad_perm:[2,3,0,1] row_mask:0xf bank_mask:0xf bound_ctrl:1
	s_nop 0
	v_mov_b32_dpp v100, v90 row_half_mirror row_mask:0xf bank_mask:0xf bound_ctrl:1
	v_mov_b32_dpp v101, v91 row_half_mirror row_mask:0xf bank_mask:0xf bound_ctrl:1
	s_and_saveexec_b64 s[28:29], s[8:9]
	s_cbranch_execz .LBB0_895
	v_pk_add_f32 v[90:91], v[90:91], v[100:101]
	v_readlane_b32 s30, v254, 9
	v_pk_fma_f32 v[90:91], v[120:121], v[126:127], v[90:91] op_sel:[0,1,0]
	v_readlane_b32 s31, v254, 10
	v_pk_fma_f32 v[90:91], v[126:127], v[88:89], v[90:91] op_sel_hi:[0,1,1] neg_lo:[1,0,0] neg_hi:[1,0,0]
	s_nop 0
	v_lshl_add_u64 v[100:101], v[134:135], 0, s[30:31]
	flat_store_dwordx2 v[100:101], v[90:91]
.LBB0_895:
	s_or_b64 exec, exec, s[28:29]
	v_pk_mul_f32 v[90:91], v[84:85], v[88:89] op_sel_hi:[1,0]
	v_pk_mul_f32 v[84:85], v[84:85], v[88:89] op_sel:[0,1]
	v_pk_fma_f32 v[90:91], v[76:77], v[120:121], v[90:91] op_sel_hi:[1,0,1] neg_lo:[0,0,1] neg_hi:[0,0,1]
	v_pk_fma_f32 v[76:77], v[76:77], v[120:121], v[84:85] op_sel:[0,1,0] neg_lo:[0,0,1] neg_hi:[0,0,1]
	v_pk_fma_f32 v[128:129], v[64:65], v[128:129], v[90:91]
	v_pk_fma_f32 v[130:131], v[64:65], v[130:131], v[76:77]
	v_pk_mul_f32 v[64:65], v[86:87], v[88:89] op_sel_hi:[1,0]
	v_pk_mul_f32 v[76:77], v[86:87], v[88:89] op_sel:[0,1]
	v_pk_fma_f32 v[64:65], v[78:79], v[120:121], v[64:65] op_sel_hi:[1,0,1] neg_lo:[0,0,1] neg_hi:[0,0,1]
	v_pk_fma_f32 v[76:77], v[78:79], v[120:121], v[76:77] op_sel:[0,1,0] neg_lo:[0,0,1] neg_hi:[0,0,1]
	v_pk_fma_f32 v[138:139], v[66:67], v[138:139], v[64:65]
	v_pk_mul_f32 v[64:65], v[60:61], v[88:89] op_sel_hi:[1,0]
	v_pk_mul_f32 v[60:61], v[60:61], v[88:89] op_sel:[0,1]
	v_pk_fma_f32 v[140:141], v[66:67], v[140:141], v[76:77]
	v_pk_fma_f32 v[64:65], v[48:49], v[120:121], v[64:65] op_sel_hi:[1,0,1] neg_lo:[0,0,1] neg_hi:[0,0,1]
	v_pk_fma_f32 v[48:49], v[48:49], v[120:121], v[60:61] op_sel:[0,1,0] neg_lo:[0,0,1] neg_hi:[0,0,1]
	v_pk_fma_f32 v[142:143], v[40:41], v[142:143], v[64:65]
	v_pk_fma_f32 v[146:147], v[40:41], v[146:147], v[48:49]
	v_pk_mul_f32 v[40:41], v[62:63], v[88:89] op_sel_hi:[1,0]
	v_pk_mul_f32 v[48:49], v[62:63], v[88:89] op_sel:[0,1]
	s_waitcnt lgkmcnt(0)
	v_pk_mul_f32 v[148:149], v[114:115], v[138:139]
	v_pk_mul_f32 v[114:115], v[114:115], v[140:141]
	v_pk_fma_f32 v[40:41], v[50:51], v[120:121], v[40:41] op_sel_hi:[1,0,1] neg_lo:[0,0,1] neg_hi:[0,0,1]
	v_pk_fma_f32 v[48:49], v[50:51], v[120:121], v[48:49] op_sel:[0,1,0] neg_lo:[0,0,1] neg_hi:[0,0,1]
	v_pk_fma_f32 v[148:149], v[112:113], v[128:129], v[148:149]
	v_pk_fma_f32 v[112:113], v[112:113], v[130:131], v[114:115]
	v_pk_mul_f32 v[114:115], v[106:107], v[138:139]
	v_pk_mul_f32 v[106:107], v[106:107], v[140:141]
	v_pk_fma_f32 v[136:137], v[42:43], v[136:137], v[40:41]
	v_pk_fma_f32 v[144:145], v[42:43], v[144:145], v[48:49]
	v_pk_fma_f32 v[114:115], v[104:105], v[128:129], v[114:115]
	v_pk_fma_f32 v[104:105], v[104:105], v[130:131], v[106:107]
	v_pk_fma_f32 v[106:107], v[92:93], v[142:143], v[148:149]
	v_pk_fma_f32 v[92:93], v[92:93], v[146:147], v[112:113]
	ds_read_b128 v[88:91], v160 offset:18832
	ds_read_b128 v[64:67], v160 offset:19072
	ds_read_b128 v[40:43], v160 offset:19088
	ds_read_b128 v[76:79], v160 offset:19328
	ds_read_b128 v[48:51], v160 offset:19344
	ds_read_b128 v[84:87], v160 offset:19584
	ds_read_b128 v[60:63], v160 offset:19600
	ds_read_b128 v[108:111], v160 offset:19840
	ds_read_b128 v[100:103], v160 offset:19856
	ds_read_b64 v[120:121], v161 offset:20096
	ds_read_b128 v[116:119], v160 offset:18816
	ds_read_b64 v[126:127], v159 offset:20352
	v_pk_fma_f32 v[112:113], v[96:97], v[142:143], v[114:115]
	v_pk_fma_f32 v[96:97], v[96:97], v[146:147], v[104:105]
	v_pk_fma_f32 v[104:105], v[94:95], v[136:137], v[106:107]
	v_pk_fma_f32 v[92:93], v[94:95], v[144:145], v[92:93]
	v_pk_fma_f32 v[94:95], v[98:99], v[136:137], v[112:113]
	v_pk_fma_f32 v[96:97], v[98:99], v[144:145], v[96:97]
	v_add_f32_e32 v93, v92, v93
	v_add_f32_e32 v92, v104, v105
	s_nop 1
	v_add_f32_dpp v92, v92, v92 quad_perm:[1,0,3,2] row_mask:0xf bank_mask:0xf bound_ctrl:1
	v_add_f32_dpp v93, v93, v93 quad_perm:[1,0,3,2] row_mask:0xf bank_mask:0xf bound_ctrl:1
	s_nop 1
	v_add_f32_e32 v94, v94, v95
	v_add_f32_e32 v95, v96, v97
	v_add_f32_dpp v92, v92, v92 quad_perm:[2,3,0,1] row_mask:0xf bank_mask:0xf bound_ctrl:1
	v_add_f32_dpp v93, v93, v93 quad_perm:[2,3,0,1] row_mask:0xf bank_mask:0xf bound_ctrl:1
	v_add_f32_dpp v94, v94, v94 quad_perm:[1,0,3,2] row_mask:0xf bank_mask:0xf bound_ctrl:1
	v_add_f32_dpp v95, v95, v95 quad_perm:[1,0,3,2] row_mask:0xf bank_mask:0xf bound_ctrl:1
	v_add_f32_dpp v92, v92, v92 row_half_mirror row_mask:0xf bank_mask:0xf bound_ctrl:1
	v_add_f32_dpp v93, v93, v93 row_half_mirror row_mask:0xf bank_mask:0xf bound_ctrl:1
	v_add_f32_dpp v94, v94, v94 quad_perm:[2,3,0,1] row_mask:0xf bank_mask:0xf bound_ctrl:1
	v_add_f32_dpp v95, v95, v95 quad_perm:[2,3,0,1] row_mask:0xf bank_mask:0xf bound_ctrl:1
	s_nop 0
	v_mov_b32_dpp v96, v94 row_half_mirror row_mask:0xf bank_mask:0xf bound_ctrl:1
	v_mov_b32_dpp v97, v95 row_half_mirror row_mask:0xf bank_mask:0xf bound_ctrl:1
	s_and_saveexec_b64 s[28:29], s[8:9]
	s_cbranch_execz .LBB0_897
	v_pk_add_f32 v[94:95], v[94:95], v[96:97]
	v_readlane_b32 s30, v254, 11
	v_pk_fma_f32 v[94:95], v[122:123], v[124:125], v[94:95] op_sel:[0,1,0]
	v_readlane_b32 s31, v254, 12
	v_pk_fma_f32 v[94:95], v[124:125], v[92:93], v[94:95] op_sel_hi:[0,1,1] neg_lo:[1,0,0] neg_hi:[1,0,0]
	s_nop 0
	v_lshl_add_u64 v[96:97], v[134:135], 0, s[30:31]
	flat_store_dwordx2 v[96:97], v[94:95]
.LBB0_897:
	s_or_b64 exec, exec, s[28:29]
	v_pk_mul_f32 v[94:95], v[80:81], v[92:93] op_sel_hi:[1,0]
	v_pk_mul_f32 v[80:81], v[80:81], v[92:93] op_sel:[0,1]
	v_pk_fma_f32 v[94:95], v[72:73], v[122:123], v[94:95] op_sel_hi:[1,0,1] neg_lo:[0,0,1] neg_hi:[0,0,1]
	v_pk_fma_f32 v[72:73], v[72:73], v[122:123], v[80:81] op_sel:[0,1,0] neg_lo:[0,0,1] neg_hi:[0,0,1]
	v_pk_fma_f32 v[128:129], v[68:69], v[128:129], v[94:95]
	v_pk_fma_f32 v[130:131], v[68:69], v[130:131], v[72:73]
	v_pk_mul_f32 v[68:69], v[82:83], v[92:93] op_sel_hi:[1,0]
	v_pk_mul_f32 v[72:73], v[82:83], v[92:93] op_sel:[0,1]
	v_pk_fma_f32 v[68:69], v[74:75], v[122:123], v[68:69] op_sel_hi:[1,0,1] neg_lo:[0,0,1] neg_hi:[0,0,1]
	v_pk_fma_f32 v[72:73], v[74:75], v[122:123], v[72:73] op_sel:[0,1,0] neg_lo:[0,0,1] neg_hi:[0,0,1]
	v_pk_fma_f32 v[138:139], v[70:71], v[138:139], v[68:69]
	v_pk_mul_f32 v[68:69], v[56:57], v[92:93] op_sel_hi:[1,0]
	v_pk_mul_f32 v[56:57], v[56:57], v[92:93] op_sel:[0,1]
	v_pk_fma_f32 v[140:141], v[70:71], v[140:141], v[72:73]
	v_pk_fma_f32 v[68:69], v[52:53], v[122:123], v[68:69] op_sel_hi:[1,0,1] neg_lo:[0,0,1] neg_hi:[0,0,1]
	v_pk_fma_f32 v[52:53], v[52:53], v[122:123], v[56:57] op_sel:[0,1,0] neg_lo:[0,0,1] neg_hi:[0,0,1]
	v_pk_fma_f32 v[142:143], v[44:45], v[142:143], v[68:69]
	v_pk_fma_f32 v[146:147], v[44:45], v[146:147], v[52:53]
	v_pk_mul_f32 v[44:45], v[58:59], v[92:93] op_sel_hi:[1,0]
	v_pk_mul_f32 v[52:53], v[58:59], v[92:93] op_sel:[0,1]
	s_waitcnt lgkmcnt(0)
	v_pk_mul_f32 v[148:149], v[118:119], v[138:139]
	v_pk_mul_f32 v[118:119], v[118:119], v[140:141]
	v_pk_fma_f32 v[44:45], v[54:55], v[122:123], v[44:45] op_sel_hi:[1,0,1] neg_lo:[0,0,1] neg_hi:[0,0,1]
	v_pk_fma_f32 v[52:53], v[54:55], v[122:123], v[52:53] op_sel:[0,1,0] neg_lo:[0,0,1] neg_hi:[0,0,1]
	v_pk_fma_f32 v[148:149], v[116:117], v[128:129], v[148:149]
	v_pk_fma_f32 v[116:117], v[116:117], v[130:131], v[118:119]
	v_pk_mul_f32 v[118:119], v[110:111], v[138:139]
	v_pk_mul_f32 v[110:111], v[110:111], v[140:141]
	v_pk_fma_f32 v[136:137], v[46:47], v[136:137], v[44:45]
	v_pk_fma_f32 v[144:145], v[46:47], v[144:145], v[52:53]
	v_pk_fma_f32 v[118:119], v[108:109], v[128:129], v[118:119]
	v_pk_fma_f32 v[108:109], v[108:109], v[130:131], v[110:111]
	v_pk_fma_f32 v[110:111], v[88:89], v[142:143], v[148:149]
	v_pk_fma_f32 v[88:89], v[88:89], v[146:147], v[116:117]
	ds_read_b128 v[92:95], v160 offset:20400
	ds_read_b128 v[68:71], v160 offset:20640
	ds_read_b128 v[44:47], v160 offset:20656
	ds_read_b128 v[72:75], v160 offset:20896
	ds_read_b128 v[52:55], v160 offset:20912
	ds_read_b128 v[80:83], v160 offset:21152
	ds_read_b128 v[56:59], v160 offset:21168
	ds_read_b128 v[104:107], v160 offset:21408
	ds_read_b128 v[96:99], v160 offset:21424
	ds_read_b64 v[122:123], v161 offset:21664
	ds_read_b128 v[112:115], v160 offset:20384
	ds_read_b64 v[124:125], v159 offset:21920
	v_pk_fma_f32 v[116:117], v[100:101], v[142:143], v[118:119]
	v_pk_fma_f32 v[100:101], v[100:101], v[146:147], v[108:109]
	v_pk_fma_f32 v[108:109], v[90:91], v[136:137], v[110:111]
	v_pk_fma_f32 v[88:89], v[90:91], v[144:145], v[88:89]
	v_pk_fma_f32 v[90:91], v[102:103], v[136:137], v[116:117]
	v_pk_fma_f32 v[100:101], v[102:103], v[144:145], v[100:101]
	v_add_f32_e32 v89, v88, v89
	v_add_f32_e32 v88, v108, v109
	s_nop 1
	v_add_f32_dpp v88, v88, v88 quad_perm:[1,0,3,2] row_mask:0xf bank_mask:0xf bound_ctrl:1
	v_add_f32_dpp v89, v89, v89 quad_perm:[1,0,3,2] row_mask:0xf bank_mask:0xf bound_ctrl:1
	s_nop 1
	v_add_f32_e32 v90, v90, v91
	v_add_f32_e32 v91, v100, v101
	v_add_f32_dpp v88, v88, v88 quad_perm:[2,3,0,1] row_mask:0xf bank_mask:0xf bound_ctrl:1
	v_add_f32_dpp v89, v89, v89 quad_perm:[2,3,0,1] row_mask:0xf bank_mask:0xf bound_ctrl:1
	v_add_f32_dpp v90, v90, v90 quad_perm:[1,0,3,2] row_mask:0xf bank_mask:0xf bound_ctrl:1
	v_add_f32_dpp v91, v91, v91 quad_perm:[1,0,3,2] row_mask:0xf bank_mask:0xf bound_ctrl:1
	v_add_f32_dpp v88, v88, v88 row_half_mirror row_mask:0xf bank_mask:0xf bound_ctrl:1
	v_add_f32_dpp v89, v89, v89 row_half_mirror row_mask:0xf bank_mask:0xf bound_ctrl:1
	v_add_f32_dpp v90, v90, v90 quad_perm:[2,3,0,1] row_mask:0xf bank_mask:0xf bound_ctrl:1
	v_add_f32_dpp v91, v91, v91 quad_perm:[2,3,0,1] row_mask:0xf bank_mask:0xf bound_ctrl:1
	s_nop 0
	v_mov_b32_dpp v100, v90 row_half_mirror row_mask:0xf bank_mask:0xf bound_ctrl:1
	v_mov_b32_dpp v101, v91 row_half_mirror row_mask:0xf bank_mask:0xf bound_ctrl:1
	s_and_saveexec_b64 s[28:29], s[8:9]
	s_cbranch_execz .LBB0_899
	v_pk_add_f32 v[90:91], v[90:91], v[100:101]
	v_readlane_b32 s30, v254, 13
	v_pk_fma_f32 v[90:91], v[120:121], v[126:127], v[90:91] op_sel:[0,1,0]
	v_readlane_b32 s31, v254, 14
	v_pk_fma_f32 v[90:91], v[126:127], v[88:89], v[90:91] op_sel_hi:[0,1,1] neg_lo:[1,0,0] neg_hi:[1,0,0]
	s_nop 0
	v_lshl_add_u64 v[100:101], v[134:135], 0, s[30:31]
	flat_store_dwordx2 v[100:101], v[90:91]
.LBB0_899:
	s_or_b64 exec, exec, s[28:29]
	v_pk_mul_f32 v[90:91], v[84:85], v[88:89] op_sel_hi:[1,0]
	v_pk_mul_f32 v[84:85], v[84:85], v[88:89] op_sel:[0,1]
	v_pk_fma_f32 v[90:91], v[76:77], v[120:121], v[90:91] op_sel_hi:[1,0,1] neg_lo:[0,0,1] neg_hi:[0,0,1]
	v_pk_fma_f32 v[76:77], v[76:77], v[120:121], v[84:85] op_sel:[0,1,0] neg_lo:[0,0,1] neg_hi:[0,0,1]
	v_pk_fma_f32 v[128:129], v[64:65], v[128:129], v[90:91]
	v_pk_fma_f32 v[130:131], v[64:65], v[130:131], v[76:77]
	v_pk_mul_f32 v[64:65], v[86:87], v[88:89] op_sel_hi:[1,0]
	v_pk_mul_f32 v[76:77], v[86:87], v[88:89] op_sel:[0,1]
	v_pk_fma_f32 v[64:65], v[78:79], v[120:121], v[64:65] op_sel_hi:[1,0,1] neg_lo:[0,0,1] neg_hi:[0,0,1]
	v_pk_fma_f32 v[76:77], v[78:79], v[120:121], v[76:77] op_sel:[0,1,0] neg_lo:[0,0,1] neg_hi:[0,0,1]
	v_pk_fma_f32 v[138:139], v[66:67], v[138:139], v[64:65]
	v_pk_mul_f32 v[64:65], v[60:61], v[88:89] op_sel_hi:[1,0]
	v_pk_mul_f32 v[60:61], v[60:61], v[88:89] op_sel:[0,1]
	v_pk_fma_f32 v[140:141], v[66:67], v[140:141], v[76:77]
	v_pk_fma_f32 v[64:65], v[48:49], v[120:121], v[64:65] op_sel_hi:[1,0,1] neg_lo:[0,0,1] neg_hi:[0,0,1]
	v_pk_fma_f32 v[48:49], v[48:49], v[120:121], v[60:61] op_sel:[0,1,0] neg_lo:[0,0,1] neg_hi:[0,0,1]
	v_pk_fma_f32 v[142:143], v[40:41], v[142:143], v[64:65]
	v_pk_fma_f32 v[146:147], v[40:41], v[146:147], v[48:49]
	v_pk_mul_f32 v[40:41], v[62:63], v[88:89] op_sel_hi:[1,0]
	v_pk_mul_f32 v[48:49], v[62:63], v[88:89] op_sel:[0,1]
	s_waitcnt lgkmcnt(0)
	v_pk_mul_f32 v[148:149], v[114:115], v[138:139]
	v_pk_mul_f32 v[114:115], v[114:115], v[140:141]
	v_pk_fma_f32 v[40:41], v[50:51], v[120:121], v[40:41] op_sel_hi:[1,0,1] neg_lo:[0,0,1] neg_hi:[0,0,1]
	v_pk_fma_f32 v[48:49], v[50:51], v[120:121], v[48:49] op_sel:[0,1,0] neg_lo:[0,0,1] neg_hi:[0,0,1]
	v_pk_fma_f32 v[148:149], v[112:113], v[128:129], v[148:149]
	v_pk_fma_f32 v[112:113], v[112:113], v[130:131], v[114:115]
	v_pk_mul_f32 v[114:115], v[106:107], v[138:139]
	v_pk_mul_f32 v[106:107], v[106:107], v[140:141]
	v_pk_fma_f32 v[136:137], v[42:43], v[136:137], v[40:41]
	v_pk_fma_f32 v[144:145], v[42:43], v[144:145], v[48:49]
	v_pk_fma_f32 v[114:115], v[104:105], v[128:129], v[114:115]
	v_pk_fma_f32 v[104:105], v[104:105], v[130:131], v[106:107]
	v_pk_fma_f32 v[106:107], v[92:93], v[142:143], v[148:149]
	v_pk_fma_f32 v[92:93], v[92:93], v[146:147], v[112:113]
	ds_read_b128 v[88:91], v160 offset:21968
	ds_read_b128 v[64:67], v160 offset:22208
	ds_read_b128 v[40:43], v160 offset:22224
	ds_read_b128 v[76:79], v160 offset:22464
	ds_read_b128 v[48:51], v160 offset:22480
	ds_read_b128 v[84:87], v160 offset:22720
	ds_read_b128 v[60:63], v160 offset:22736
	ds_read_b128 v[108:111], v160 offset:22976
	ds_read_b128 v[100:103], v160 offset:22992
	ds_read_b64 v[120:121], v161 offset:23232
	ds_read_b128 v[116:119], v160 offset:21952
	ds_read_b64 v[126:127], v159 offset:23488
	v_pk_fma_f32 v[112:113], v[96:97], v[142:143], v[114:115]
	v_pk_fma_f32 v[96:97], v[96:97], v[146:147], v[104:105]
	v_pk_fma_f32 v[104:105], v[94:95], v[136:137], v[106:107]
	v_pk_fma_f32 v[92:93], v[94:95], v[144:145], v[92:93]
	v_pk_fma_f32 v[94:95], v[98:99], v[136:137], v[112:113]
	v_pk_fma_f32 v[96:97], v[98:99], v[144:145], v[96:97]
	v_add_f32_e32 v93, v92, v93
	v_add_f32_e32 v92, v104, v105
	s_nop 1
	v_add_f32_dpp v92, v92, v92 quad_perm:[1,0,3,2] row_mask:0xf bank_mask:0xf bound_ctrl:1
	v_add_f32_dpp v93, v93, v93 quad_perm:[1,0,3,2] row_mask:0xf bank_mask:0xf bound_ctrl:1
	s_nop 1
	v_add_f32_e32 v94, v94, v95
	v_add_f32_e32 v95, v96, v97
	v_add_f32_dpp v92, v92, v92 quad_perm:[2,3,0,1] row_mask:0xf bank_mask:0xf bound_ctrl:1
	v_add_f32_dpp v93, v93, v93 quad_perm:[2,3,0,1] row_mask:0xf bank_mask:0xf bound_ctrl:1
	v_add_f32_dpp v94, v94, v94 quad_perm:[1,0,3,2] row_mask:0xf bank_mask:0xf bound_ctrl:1
	v_add_f32_dpp v95, v95, v95 quad_perm:[1,0,3,2] row_mask:0xf bank_mask:0xf bound_ctrl:1
	v_add_f32_dpp v92, v92, v92 row_half_mirror row_mask:0xf bank_mask:0xf bound_ctrl:1
	v_add_f32_dpp v93, v93, v93 row_half_mirror row_mask:0xf bank_mask:0xf bound_ctrl:1
	v_add_f32_dpp v94, v94, v94 quad_perm:[2,3,0,1] row_mask:0xf bank_mask:0xf bound_ctrl:1
	v_add_f32_dpp v95, v95, v95 quad_perm:[2,3,0,1] row_mask:0xf bank_mask:0xf bound_ctrl:1
	s_nop 0
	v_mov_b32_dpp v96, v94 row_half_mirror row_mask:0xf bank_mask:0xf bound_ctrl:1
	v_mov_b32_dpp v97, v95 row_half_mirror row_mask:0xf bank_mask:0xf bound_ctrl:1
	s_and_saveexec_b64 s[28:29], s[8:9]
	s_cbranch_execz .LBB0_901
	v_pk_add_f32 v[94:95], v[94:95], v[96:97]
	v_readlane_b32 s30, v254, 15
	v_pk_fma_f32 v[94:95], v[122:123], v[124:125], v[94:95] op_sel:[0,1,0]
	v_readlane_b32 s31, v254, 16
	v_pk_fma_f32 v[94:95], v[124:125], v[92:93], v[94:95] op_sel_hi:[0,1,1] neg_lo:[1,0,0] neg_hi:[1,0,0]
	s_nop 0
	v_lshl_add_u64 v[96:97], v[134:135], 0, s[30:31]
	flat_store_dwordx2 v[96:97], v[94:95]
.LBB0_901:
	s_or_b64 exec, exec, s[28:29]
	v_pk_mul_f32 v[94:95], v[80:81], v[92:93] op_sel_hi:[1,0]
	v_pk_mul_f32 v[80:81], v[80:81], v[92:93] op_sel:[0,1]
	v_pk_fma_f32 v[94:95], v[72:73], v[122:123], v[94:95] op_sel_hi:[1,0,1] neg_lo:[0,0,1] neg_hi:[0,0,1]
	v_pk_fma_f32 v[72:73], v[72:73], v[122:123], v[80:81] op_sel:[0,1,0] neg_lo:[0,0,1] neg_hi:[0,0,1]
	v_pk_fma_f32 v[128:129], v[68:69], v[128:129], v[94:95]
	v_pk_fma_f32 v[130:131], v[68:69], v[130:131], v[72:73]
	v_pk_mul_f32 v[68:69], v[82:83], v[92:93] op_sel_hi:[1,0]
	v_pk_mul_f32 v[72:73], v[82:83], v[92:93] op_sel:[0,1]
	v_pk_fma_f32 v[68:69], v[74:75], v[122:123], v[68:69] op_sel_hi:[1,0,1] neg_lo:[0,0,1] neg_hi:[0,0,1]
	v_pk_fma_f32 v[72:73], v[74:75], v[122:123], v[72:73] op_sel:[0,1,0] neg_lo:[0,0,1] neg_hi:[0,0,1]
	v_pk_fma_f32 v[138:139], v[70:71], v[138:139], v[68:69]
	v_pk_mul_f32 v[68:69], v[56:57], v[92:93] op_sel_hi:[1,0]
	v_pk_mul_f32 v[56:57], v[56:57], v[92:93] op_sel:[0,1]
	v_pk_fma_f32 v[140:141], v[70:71], v[140:141], v[72:73]
	v_pk_fma_f32 v[68:69], v[52:53], v[122:123], v[68:69] op_sel_hi:[1,0,1] neg_lo:[0,0,1] neg_hi:[0,0,1]
	v_pk_fma_f32 v[52:53], v[52:53], v[122:123], v[56:57] op_sel:[0,1,0] neg_lo:[0,0,1] neg_hi:[0,0,1]
	v_pk_fma_f32 v[142:143], v[44:45], v[142:143], v[68:69]
	v_pk_fma_f32 v[146:147], v[44:45], v[146:147], v[52:53]
	v_pk_mul_f32 v[44:45], v[58:59], v[92:93] op_sel_hi:[1,0]
	v_pk_mul_f32 v[52:53], v[58:59], v[92:93] op_sel:[0,1]
	s_waitcnt lgkmcnt(0)
	v_pk_mul_f32 v[148:149], v[118:119], v[138:139]
	v_pk_mul_f32 v[118:119], v[118:119], v[140:141]
	v_pk_fma_f32 v[44:45], v[54:55], v[122:123], v[44:45] op_sel_hi:[1,0,1] neg_lo:[0,0,1] neg_hi:[0,0,1]
	v_pk_fma_f32 v[52:53], v[54:55], v[122:123], v[52:53] op_sel:[0,1,0] neg_lo:[0,0,1] neg_hi:[0,0,1]
	v_pk_fma_f32 v[148:149], v[116:117], v[128:129], v[148:149]
	v_pk_fma_f32 v[116:117], v[116:117], v[130:131], v[118:119]
	v_pk_mul_f32 v[118:119], v[110:111], v[138:139]
	v_pk_mul_f32 v[110:111], v[110:111], v[140:141]
	v_pk_fma_f32 v[136:137], v[46:47], v[136:137], v[44:45]
	v_pk_fma_f32 v[144:145], v[46:47], v[144:145], v[52:53]
	v_pk_fma_f32 v[118:119], v[108:109], v[128:129], v[118:119]
	v_pk_fma_f32 v[108:109], v[108:109], v[130:131], v[110:111]
	v_pk_fma_f32 v[110:111], v[88:89], v[142:143], v[148:149]
	v_pk_fma_f32 v[88:89], v[88:89], v[146:147], v[116:117]
	ds_read_b128 v[92:95], v160 offset:23536
	ds_read_b128 v[52:55], v160 offset:23776
	ds_read_b128 v[56:59], v160 offset:23792
	ds_read_b128 v[44:47], v160 offset:24032
	ds_read_b128 v[68:71], v160 offset:24048
	ds_read_b128 v[80:83], v160 offset:24288
	ds_read_b128 v[72:75], v160 offset:24304
	ds_read_b128 v[104:107], v160 offset:24544
	ds_read_b128 v[96:99], v160 offset:24560
	ds_read_b64 v[122:123], v161 offset:24800
	ds_read_b128 v[112:115], v160 offset:23520
	ds_read_b64 v[124:125], v159 offset:25056
	v_pk_fma_f32 v[116:117], v[100:101], v[142:143], v[118:119]
	v_pk_fma_f32 v[100:101], v[100:101], v[146:147], v[108:109]
	v_pk_fma_f32 v[108:109], v[90:91], v[136:137], v[110:111]
	v_pk_fma_f32 v[88:89], v[90:91], v[144:145], v[88:89]
	v_pk_fma_f32 v[90:91], v[102:103], v[136:137], v[116:117]
	v_pk_fma_f32 v[100:101], v[102:103], v[144:145], v[100:101]
	v_add_f32_e32 v89, v88, v89
	v_add_f32_e32 v88, v108, v109
	s_nop 1
	v_add_f32_dpp v88, v88, v88 quad_perm:[1,0,3,2] row_mask:0xf bank_mask:0xf bound_ctrl:1
	v_add_f32_dpp v89, v89, v89 quad_perm:[1,0,3,2] row_mask:0xf bank_mask:0xf bound_ctrl:1
	s_nop 1
	v_add_f32_e32 v90, v90, v91
	v_add_f32_e32 v91, v100, v101
	v_add_f32_dpp v88, v88, v88 quad_perm:[2,3,0,1] row_mask:0xf bank_mask:0xf bound_ctrl:1
	v_add_f32_dpp v89, v89, v89 quad_perm:[2,3,0,1] row_mask:0xf bank_mask:0xf bound_ctrl:1
	v_add_f32_dpp v90, v90, v90 quad_perm:[1,0,3,2] row_mask:0xf bank_mask:0xf bound_ctrl:1
	v_add_f32_dpp v91, v91, v91 quad_perm:[1,0,3,2] row_mask:0xf bank_mask:0xf bound_ctrl:1
	v_add_f32_dpp v88, v88, v88 row_half_mirror row_mask:0xf bank_mask:0xf bound_ctrl:1
	v_add_f32_dpp v89, v89, v89 row_half_mirror row_mask:0xf bank_mask:0xf bound_ctrl:1
	v_add_f32_dpp v90, v90, v90 quad_perm:[2,3,0,1] row_mask:0xf bank_mask:0xf bound_ctrl:1
	v_add_f32_dpp v91, v91, v91 quad_perm:[2,3,0,1] row_mask:0xf bank_mask:0xf bound_ctrl:1
	s_nop 0
	v_mov_b32_dpp v100, v90 row_half_mirror row_mask:0xf bank_mask:0xf bound_ctrl:1
	v_mov_b32_dpp v101, v91 row_half_mirror row_mask:0xf bank_mask:0xf bound_ctrl:1
	s_and_saveexec_b64 s[28:29], s[8:9]
	s_cbranch_execz .LBB0_903
	v_pk_add_f32 v[90:91], v[90:91], v[100:101]
	v_readlane_b32 s30, v254, 17
	v_pk_fma_f32 v[90:91], v[120:121], v[126:127], v[90:91] op_sel:[0,1,0]
	v_readlane_b32 s31, v254, 18
	v_pk_fma_f32 v[90:91], v[126:127], v[88:89], v[90:91] op_sel_hi:[0,1,1] neg_lo:[1,0,0] neg_hi:[1,0,0]
	s_nop 0
	v_lshl_add_u64 v[100:101], v[134:135], 0, s[30:31]
	flat_store_dwordx2 v[100:101], v[90:91]
